# addon_v44
# speedup vs baseline: 1.0181x; 1.0172x over previous
; __device__ __forceinline__ void p0_prologue(const Args& a, LAS unsigned char* lds, int wave, int lane) {
;     ...
;         bf16_t* XB = (bf16_t*)(a.ws + WS_XB);
;         const int gw = blockIdx.x * 2 + (wave - 6), NGW = gridDim.x * 2;
;         f32x4 va[4][4], vb[4][4];
;         int m0 = gw;
;         if (m0 < T) p0_load4(a, m0, NGW, lane, va);
.LBB0_17:
	s_lshr_b32 s3, s48, 6
	s_cmp_lt_i32 s66, 1
	s_cselect_b64 s[0:1], -1, 0
	s_cmp_gt_i32 s67, 0
	s_cselect_b64 s[4:5], -1, 0
	s_and_b64 s[4:5], s[0:1], s[4:5]
	s_andn2_b64 vcc, exec, s[4:5]
	v_and_b32_e32 v191, 63, v190
	s_cbranch_vccnz .LBB0_106
	s_cmpk_gt_u32 s48, 0x17f
	s_mov_b64 s[0:1], -1
	s_cbranch_scc0 .LBB0_41
	s_load_dword s6, s[74:75], 0x80
	s_lshl_b32 s12, s2, 1
	s_add_i32 s10, s12, s3
	s_add_i32 s10, s10, -6
	s_cmp_lt_i32 s10, 0x4000
	s_waitcnt lgkmcnt(0)
	s_mul_i32 s8, s6, 6
	s_cbranch_scc1 .LBB0_21
	s_lshl_b32 s7, s6, 2
	s_mul_i32 s9, s6, 6
	s_mov_b64 s[0:1], 0
	s_andn2_b64 vcc, exec, s[0:1]
	v_lshlrev_b32_e32 v130, 4, v191
	s_cbranch_vccnz .LBB0_23
	s_branch .LBB0_22

; __device__ __forceinline__ void p0_load4(const Args& a, int m0, int NGW, int lane, f32x4 (&v)[4][4]) {
; #pragma unroll
;     for (int u = 0; u < 4; ++u) { const int m = min(m0 + u * NGW, T - 1);
;         const float* xrow = m < TP ? a.in[0] + (size_t)m * 1024 : a.in[1] + (size_t)(m - TP) * 1024;
;         const f32x4* xr = (const f32x4*)xrow + lane;
; #pragma unroll
;         for (int j = 0; j < 4; ++j) v[u][j] = xr[64 * j]; }
; }
.LBB0_22:
	s_lshl_b32 s9, s6, 1
	s_add_i32 s0, s10, 0xffff8000
	s_ashr_i32 s1, s10, 31
	s_cmp_lt_i32 s10, 0x8000
	s_cselect_b32 s1, s1, 0
	s_cselect_b32 s0, s10, s0
	s_cselect_b32 s7, s77, s79
	s_cselect_b32 s11, s76, s78
	s_lshl_b64 s[0:1], s[0:1], 12
	s_add_u32 s0, s11, s0
	s_addc_u32 s1, s7, s1
	s_add_i32 s10, s9, s10
	global_load_dwordx4 v[0:3], v130, s[0:1]
	global_load_dwordx4 v[4:7], v130, s[0:1] offset:1024
	global_load_dwordx4 v[8:11], v130, s[0:1] offset:2048
	global_load_dwordx4 v[12:15], v130, s[0:1] offset:3072
	s_min_i32 s0, s10, 0x3fff
	s_ashr_i32 s1, s0, 31
	s_add_i32 s7, s0, 0xffff8000
	s_cmp_lt_i32 s10, 0x8000
	s_cselect_b32 s1, s1, 0
	s_cselect_b32 s0, s0, s7
	s_cselect_b32 s7, s77, s79
	s_cselect_b32 s11, s76, s78
	s_lshl_b64 s[0:1], s[0:1], 12
	s_add_u32 s0, s11, s0
	s_addc_u32 s1, s7, s1
	s_add_i32 s10, s10, s9
	global_load_dwordx4 v[16:19], v130, s[0:1]
	global_load_dwordx4 v[20:23], v130, s[0:1] offset:1024
	global_load_dwordx4 v[24:27], v130, s[0:1] offset:2048
	global_load_dwordx4 v[28:31], v130, s[0:1] offset:3072
	s_min_i32 s0, s10, 0x3fff
	s_lshl_b32 s7, s6, 2
	s_ashr_i32 s1, s0, 31
	s_add_i32 s11, s0, 0xffff8000
	s_cmp_lt_i32 s10, 0x8000
	s_cselect_b32 s1, s1, 0
	s_cselect_b32 s0, s0, s11
	s_cselect_b32 s11, s77, s79
	s_cselect_b32 s13, s76, s78
	s_lshl_b64 s[0:1], s[0:1], 12
	s_add_u32 s0, s13, s0
	s_addc_u32 s1, s11, s1
	s_add_i32 s10, s10, s9
	global_load_dwordx4 v[32:35], v130, s[0:1]
	global_load_dwordx4 v[36:39], v130, s[0:1] offset:1024
	global_load_dwordx4 v[40:43], v130, s[0:1] offset:2048
	global_load_dwordx4 v[44:47], v130, s[0:1] offset:3072
	s_min_i32 s0, s10, 0x3fff
	s_ashr_i32 s1, s0, 31
	s_add_i32 s9, s0, 0xffff8000
	s_cmp_lt_i32 s10, 0x8000
	s_cselect_b32 s1, s1, 0
	s_cselect_b32 s0, s0, s9
	s_cselect_b32 s9, s77, s79
	s_cselect_b32 s10, s76, s78
	s_lshl_b64 s[0:1], s[0:1], 12
	s_add_u32 s0, s10, s0
	s_addc_u32 s1, s9, s1
	global_load_dwordx4 v[48:51], v130, s[0:1]
	global_load_dwordx4 v[52:55], v130, s[0:1] offset:1024
	global_load_dwordx4 v[56:59], v130, s[0:1] offset:2048
	global_load_dwordx4 v[60:63], v130, s[0:1] offset:3072
	s_mov_b32 s9, s8

; __device__ __forceinline__ void p0_prologue(const Args& a, LAS unsigned char* lds, int wave, int lane) {
;     ...
;         while (m0 < T) {
;             const int m1 = m0 + 4 * NGW; const bool has1 = m1 < T;
;             if (has1) p0_load4(a, m1, NGW, lane, vb);
.LBB0_24:
	s_add_i32 s26, s26, s14
	s_add_i32 s0, s12, s26
	s_add_i32 s0, s0, -6
	s_cmp_gt_i32 s0, 0x3fff
	s_cselect_b64 s[0:1], -1, 0

; __device__ __forceinline__ void p0_proc4(bf16_t* XB, int m0, int NGW, int lane, const f32x4 (&v)[4][4]) {
;     float s[4];
; #pragma unroll
;     for (int u = 0; u < 4; ++u) { float t = 0.f;
; #pragma unroll
;         for (int j = 0; j < 4; ++j) t += (v[u][j][0] * v[u][j][0] + v[u][j][1] * v[u][j][1]) + (v[u][j][2] * v[u][j][2] + v[u][j][3] * v[u][j][3]);
;         s[u] = t; }
; #pragma unroll
;     for (int o = 1; o < 64; o <<= 1) {
; #pragma unroll
;         for (int u = 0; u < 4; ++u) s[u] += __shfl_xor(s[u], o); }
; __device__ __forceinline__ void p0_prologue(const Args& a, LAS unsigned char* lds, int wave, int lane) {
;     ...
;             const int m1 = m0 + 4 * NGW; const bool has1 = m1 < T;
;             if (has1) p0_load4(a, m1, NGW, lane, vb);
;             p0_proc4(XB, m0, NGW, lane, va);
;             if (!has1) break;
;             const int m2 = m1 + 4 * NGW; const bool has2 = m2 < T;
;             if (has2) p0_load4(a, m2, NGW, lane, va);
;             p0_proc4(XB, m1, NGW, lane, vb);
.LBB0_26:
	s_add_i32 s0, s12, s26
	s_add_i32 s10, s0, -6
	s_cmp_gt_i32 s10, 0x3fff
	s_mov_b64 s[0:1], -1
	s_cbranch_scc1 .LBB0_25
	s_add_i32 s0, s20, s26
	s_add_i32 s6, s0, -6
	s_cmp_lt_i32 s6, 0x4000
	s_cselect_b64 s[8:9], -1, 0
	s_cmp_gt_i32 s6, 0x3fff
	s_cbranch_scc1 .LBB0_29
	s_add_i32 s0, s0, 0xffff7ffa
	s_ashr_i32 s1, s6, 31
	s_cmp_lt_i32 s6, 0x8000
	s_cselect_b32 s1, s1, 0
	s_cselect_b32 s0, s6, s0
	s_cselect_b32 s7, s77, s79
	s_cselect_b32 s11, s76, s78
	s_lshl_b64 s[0:1], s[0:1], 12
	s_add_u32 s0, s11, s0
	s_addc_u32 s1, s7, s1
	global_load_dwordx4 v[76:79], v130, s[0:1]
	global_load_dwordx4 v[72:75], v130, s[0:1] offset:1024
	global_load_dwordx4 v[68:71], v130, s[0:1] offset:2048
	global_load_dwordx4 v[64:67], v130, s[0:1] offset:3072
	s_add_i32 s0, s15, s26
	s_min_i32 s7, s0, 0x3fff
	s_ashr_i32 s1, s7, 31
	s_add_i32 s11, s7, 0xffff8000
	s_cmp_lt_i32 s0, 0x8000
	s_cselect_b32 s1, s1, 0
	s_cselect_b32 s0, s7, s11
	s_cselect_b32 s7, s77, s79
	s_cselect_b32 s11, s76, s78
	s_lshl_b64 s[0:1], s[0:1], 12
	s_add_u32 s0, s11, s0
	s_addc_u32 s1, s7, s1
	global_load_dwordx4 v[92:95], v130, s[0:1]
	global_load_dwordx4 v[88:91], v130, s[0:1] offset:1024
	global_load_dwordx4 v[84:87], v130, s[0:1] offset:2048
	global_load_dwordx4 v[80:83], v130, s[0:1] offset:3072
	s_add_i32 s0, s21, s26
	s_min_i32 s7, s0, 0x3fff
	s_ashr_i32 s1, s7, 31
	s_add_i32 s11, s7, 0xffff8000
	s_cmp_lt_i32 s0, 0x8000
	s_cselect_b32 s1, s1, 0
	s_cselect_b32 s0, s7, s11
	s_cselect_b32 s7, s77, s79
	s_cselect_b32 s11, s76, s78
	s_lshl_b64 s[0:1], s[0:1], 12
	s_add_u32 s0, s11, s0
	s_addc_u32 s1, s7, s1
	global_load_dwordx4 v[108:111], v130, s[0:1]
	global_load_dwordx4 v[104:107], v130, s[0:1] offset:1024
	global_load_dwordx4 v[100:103], v130, s[0:1] offset:2048
	global_load_dwordx4 v[96:99], v130, s[0:1] offset:3072
	s_add_i32 s0, s22, s26
	s_min_i32 s7, s0, 0x3fff
	s_ashr_i32 s1, s7, 31
	s_add_i32 s11, s7, 0xffff8000
	s_cmp_lt_i32 s0, 0x8000
	s_cselect_b32 s1, s1, 0
	s_cselect_b32 s0, s7, s11
	s_cselect_b32 s7, s77, s79
	s_cselect_b32 s11, s76, s78
	s_lshl_b64 s[0:1], s[0:1], 12
	s_add_u32 s0, s11, s0
	s_addc_u32 s1, s7, s1
	global_load_dwordx4 v[124:127], v130, s[0:1]
	global_load_dwordx4 v[120:123], v130, s[0:1] offset:1024
	global_load_dwordx4 v[116:119], v130, s[0:1] offset:2048
	global_load_dwordx4 v[112:115], v130, s[0:1] offset:3072
.LBB0_29:
	s_waitcnt vmcnt(15) lgkmcnt(0)
	v_pk_mul_f32 v[134:135], v[2:3], v[2:3]
	v_pk_mul_f32 v[136:137], v[0:1], v[0:1]
	s_waitcnt vmcnt(0)
	v_mul_f32_e32 v142, v63, v63
	v_pk_mov_b32 v[138:139], v[136:137], v[134:135] op_sel:[1,0]
	v_mov_b32_e32 v137, v135
	v_pk_add_f32 v[134:135], v[138:139], v[136:137]
	v_pk_mul_f32 v[136:137], v[6:7], v[6:7]
	v_pk_add_f32 v[134:135], v[134:135], v[134:135] op_sel_hi:[0,1]
	v_pk_mul_f32 v[138:139], v[4:5], v[4:5]
	v_mul_f32_e32 v134, v8, v8
	v_pk_mov_b32 v[140:141], v[138:139], v[136:137] op_sel:[1,0]
	v_mov_b32_e32 v139, v137
	v_pk_add_f32 v[136:137], v[140:141], v[138:139]
	v_pk_fma_f32 v[138:139], v[8:9], v[8:9], v[134:135] op_sel_hi:[1,1,0]
	v_mul_f32_e32 v134, v10, v10
	v_pk_add_f32 v[136:137], v[136:137], v[136:137] op_sel_hi:[0,1]
	v_pk_fma_f32 v[140:141], v[10:11], v[10:11], v[134:135] op_sel_hi:[1,1,0]
	v_mul_f32_e32 v138, v12, v12
	v_mul_f32_e32 v140, v13, v13
	v_mul_f32_e32 v136, v14, v14
	v_mul_f32_e32 v134, v15, v15
	v_pk_add_f32 v[138:139], v[138:139], v[140:141]
	v_pk_add_f32 v[134:135], v[136:137], v[134:135]
	v_mul_f32_e32 v136, v19, v19
	v_pk_add_f32 v[134:135], v[138:139], v[134:135]
	v_fmac_f32_e32 v136, v18, v18
	v_add_f32_e32 v134, v134, v135
	v_mul_f32_e32 v135, v17, v17
	v_fmac_f32_e32 v135, v16, v16
	v_add_f32_e32 v135, v135, v136
	v_mul_f32_e32 v136, v21, v21
	v_mul_f32_e32 v137, v23, v23
	v_fmac_f32_e32 v136, v20, v20
	v_fmac_f32_e32 v137, v22, v22
	v_add_f32_e32 v136, v136, v137
	v_add_f32_e32 v135, v136, v135
	v_mul_f32_e32 v136, v25, v25
	v_mul_f32_e32 v137, v27, v27
	v_fmac_f32_e32 v136, v24, v24
	v_fmac_f32_e32 v137, v26, v26
	v_add_f32_e32 v136, v136, v137
	v_add_f32_e32 v135, v136, v135
	v_mul_f32_e32 v136, v29, v29
	v_mul_f32_e32 v137, v31, v31
	v_fmac_f32_e32 v136, v28, v28
	v_fmac_f32_e32 v137, v30, v30
	v_add_f32_e32 v136, v136, v137
	v_add_f32_e32 v137, v136, v135
	v_mul_f32_e32 v135, v33, v33
	v_mul_f32_e32 v136, v35, v35
	v_fmac_f32_e32 v135, v32, v32
	v_fmac_f32_e32 v136, v34, v34
	v_add_f32_e32 v135, v135, v136
	v_mul_f32_e32 v136, v37, v37
	v_mul_f32_e32 v138, v39, v39
	v_fmac_f32_e32 v136, v36, v36
	v_fmac_f32_e32 v138, v38, v38
	v_add_f32_e32 v136, v136, v138
	v_add_f32_e32 v135, v136, v135
	v_mul_f32_e32 v136, v41, v41
	v_mul_f32_e32 v138, v43, v43
	v_fmac_f32_e32 v136, v40, v40
	v_fmac_f32_e32 v138, v42, v42
	v_add_f32_e32 v136, v136, v138
	v_add_f32_e32 v135, v136, v135
	v_mul_f32_e32 v136, v45, v45
	v_mul_f32_e32 v138, v47, v47
	v_fmac_f32_e32 v136, v44, v44
	v_fmac_f32_e32 v138, v46, v46
	v_add_f32_e32 v136, v136, v138
	v_add_f32_e32 v138, v136, v135
	v_mul_f32_e32 v135, v49, v49
	v_mul_f32_e32 v136, v51, v51
	v_fmac_f32_e32 v135, v48, v48
	v_fmac_f32_e32 v136, v50, v50
	v_add_f32_e32 v135, v135, v136
	v_mul_f32_e32 v136, v53, v53
	v_mul_f32_e32 v139, v55, v55
	v_fmac_f32_e32 v136, v52, v52
	v_fmac_f32_e32 v139, v54, v54
	v_add_f32_e32 v136, v136, v139
	v_add_f32_e32 v135, v136, v135
	v_mul_f32_e32 v136, v57, v57
	v_mul_f32_e32 v139, v59, v59
	v_fmac_f32_e32 v136, v56, v56
	v_fmac_f32_e32 v139, v58, v58
	v_add_f32_e32 v136, v136, v139
	v_add_f32_e32 v139, v136, v135
	v_and_b32_e32 v135, 64, v133
	v_add_u32_e32 v140, 64, v135
	v_xor_b32_e32 v135, 1, v133
	v_cmp_lt_i32_e32 vcc, v135, v140
	v_mul_f32_e32 v136, v61, v61
	v_fmac_f32_e32 v136, v60, v60
	v_cndmask_b32_e32 v135, v133, v135, vcc
	v_lshlrev_b32_e32 v135, 2, v135
	ds_bpermute_b32 v141, v135, v134
	v_fmac_f32_e32 v142, v62, v62
	v_add_f32_e32 v142, v136, v142
	v_xor_b32_e32 v136, 2, v133
	v_cmp_lt_i32_e32 vcc, v136, v140
	s_waitcnt lgkmcnt(0)
; __device__ __forceinline__ unsigned cvt_pk_bf16(float lo, float hi) { const f32x2_t v = {lo, hi}; const bf16x2_t r = __builtin_convertvector(v, bf16x2_t); return __builtin_bit_cast(unsigned, r); }
; __device__ __forceinline__ void p0_proc4(bf16_t* XB, int m0, int NGW, int lane, const f32x4 (&v)[4][4]) {
;     ...
; #pragma unroll
;     for (int o = 1; o < 64; o <<= 1) {
; #pragma unroll
;         for (int u = 0; u < 4; ++u) s[u] += __shfl_xor(s[u], o); }
; #pragma unroll
;     for (int u = 0; u < 4; ++u) { const int m = m0 + u * NGW; if (m >= T) break;
;         const float rstd = 1.0f / sqrtf(s[u] * (1.0f / 1024.0f) + NORM_EPS);
;         u32x2* o8 = (u32x2*)(XB + (size_t)m * 1024) + lane;
; #pragma unroll
;         for (int j = 0; j < 4; ++j) { u32x2 w; w.x = cvt_pk_bf16(v[u][j][0] * rstd, v[u][j][1] * rstd); w.y = cvt_pk_bf16(v[u][j][2] * rstd, v[u][j][3] * rstd); o8[64 * j] = w; } }
	v_add_f32_e32 v134, v134, v141
	ds_bpermute_b32 v141, v135, v137
	v_cndmask_b32_e32 v136, v133, v136, vcc
	ds_bpermute_b32 v143, v135, v138
	v_lshlrev_b32_e32 v136, 2, v136
	ds_bpermute_b32 v144, v136, v134
	v_add_f32_e32 v139, v142, v139
	s_waitcnt lgkmcnt(2)
	v_add_f32_e32 v141, v137, v141
	s_waitcnt lgkmcnt(1)
	v_add_f32_e32 v138, v138, v143
	v_xor_b32_e32 v137, 4, v133
	ds_bpermute_b32 v142, v135, v139
	s_waitcnt lgkmcnt(1)
	v_add_f32_e32 v134, v134, v144
	ds_bpermute_b32 v144, v136, v138
	v_cmp_lt_i32_e32 vcc, v137, v140
	ds_bpermute_b32 v143, v136, v141
	s_waitcnt lgkmcnt(2)
	v_add_f32_e32 v139, v139, v142
	v_cndmask_b32_e32 v137, v133, v137, vcc
	v_lshlrev_b32_e32 v137, 2, v137
	ds_bpermute_b32 v145, v137, v134
	s_waitcnt lgkmcnt(2)
	v_add_f32_e32 v142, v138, v144
	v_xor_b32_e32 v138, 8, v133
	s_waitcnt lgkmcnt(1)
	v_add_f32_e32 v141, v141, v143
	ds_bpermute_b32 v143, v136, v139
	v_cmp_lt_i32_e32 vcc, v138, v140
	s_waitcnt lgkmcnt(1)
	v_add_f32_e32 v134, v134, v145
	ds_bpermute_b32 v144, v137, v141
	v_cndmask_b32_e32 v138, v133, v138, vcc
	v_lshlrev_b32_e32 v138, 2, v138
	ds_bpermute_b32 v146, v138, v134
	ds_bpermute_b32 v145, v137, v142
	s_waitcnt lgkmcnt(3)
	v_add_f32_e32 v143, v139, v143
	v_xor_b32_e32 v139, 16, v133
	v_cmp_lt_i32_e32 vcc, v139, v140
	s_waitcnt lgkmcnt(2)
	v_add_f32_e32 v141, v141, v144
	s_waitcnt lgkmcnt(1)
	v_add_f32_e32 v134, v134, v146
	v_cndmask_b32_e32 v139, v133, v139, vcc
	v_lshlrev_b32_e32 v139, 2, v139
	s_waitcnt lgkmcnt(0)
	v_add_f32_e32 v142, v142, v145
	ds_bpermute_b32 v145, v138, v141
	ds_bpermute_b32 v147, v139, v134
	ds_bpermute_b32 v144, v137, v143
	ds_bpermute_b32 v146, v138, v142
	s_ashr_i32 s11, s10, 31
	s_waitcnt lgkmcnt(3)
	v_add_f32_e32 v141, v141, v145
	s_waitcnt lgkmcnt(2)
	v_add_f32_e32 v145, v134, v147
	v_xor_b32_e32 v134, 32, v133
	v_cmp_lt_i32_e32 vcc, v134, v140
	s_waitcnt lgkmcnt(1)
	v_add_f32_e32 v143, v143, v144
	ds_bpermute_b32 v144, v138, v143
	v_cndmask_b32_e32 v134, v133, v134, vcc
	v_lshlrev_b32_e32 v134, 2, v134
	ds_bpermute_b32 v140, v134, v145
	s_waitcnt lgkmcnt(2)
	v_add_f32_e32 v142, v142, v146
	s_waitcnt lgkmcnt(1)
	v_add_f32_e32 v143, v143, v144
	ds_bpermute_b32 v144, v139, v141
	ds_bpermute_b32 v147, v139, v143
	s_waitcnt lgkmcnt(2)
	v_add_f32_e32 v140, v145, v140
	v_fmamk_f32 v140, v140, 0x3a800000, v131
	v_mul_f32_e32 v145, 0x4f800000, v140
	v_cmp_gt_f32_e32 vcc, s25, v140
	ds_bpermute_b32 v146, v139, v142
	s_waitcnt lgkmcnt(2)
	v_add_f32_e32 v144, v141, v144
	v_cndmask_b32_e32 v145, v140, v145, vcc
	v_sqrt_f32_e32 v148, v145
	s_waitcnt lgkmcnt(1)
	v_add_f32_e32 v140, v143, v147
	s_waitcnt lgkmcnt(0)
	v_add_f32_e32 v142, v142, v146
	v_add_u32_e32 v141, -1, v148
	v_fma_f32 v143, -v141, v148, v145
	v_cmp_ge_f32_e64 s[0:1], 0, v143
	v_add_u32_e32 v143, 1, v148
	v_fma_f32 v146, -v143, v148, v145
	v_cndmask_b32_e64 v141, v148, v141, s[0:1]
	v_cmp_lt_f32_e64 s[0:1], 0, v146
	s_nop 1
	v_cndmask_b32_e64 v141, v141, v143, s[0:1]
	v_mul_f32_e32 v143, 0x37800000, v141
	v_cndmask_b32_e32 v141, v141, v143, vcc
	v_cmp_class_f32_e32 vcc, v145, v132
	ds_bpermute_b32 v143, v134, v142
	s_nop 0
	v_cndmask_b32_e32 v146, v141, v145, vcc
	v_div_scale_f32 v147, s[0:1], v146, v146, 1.0
	v_rcp_f32_e32 v148, v147
	s_lshl_b64 s[0:1], s[10:11], 11
	ds_bpermute_b32 v145, v134, v144
	ds_bpermute_b32 v141, v134, v140
	v_fma_f32 v149, -v147, v148, 1.0
	v_fmac_f32_e32 v148, v149, v148
	v_div_scale_f32 v149, vcc, 1.0, v146, 1.0
	v_mul_f32_e32 v150, v149, v148
	v_fma_f32 v151, -v147, v150, v149
	v_fmac_f32_e32 v150, v151, v148
	v_fma_f32 v147, -v147, v150, v149
	v_div_fmas_f32 v147, v147, v148, v150
	v_div_fixup_f32 v146, v147, v146, 1.0
	v_pk_mul_f32 v[150:151], v[0:1], v[146:147] op_sel_hi:[1,0]
	v_pk_mul_f32 v[152:153], v[2:3], v[146:147] op_sel_hi:[1,0]
	v_lshl_add_u64 v[148:149], v[128:129], 0, s[0:1]
	v_cvt_pk_bf16_f32 v150, v150, v151
	v_cvt_pk_bf16_f32 v151, v152, v153
	global_store_dwordx2 v[148:149], v[150:151], off
	v_pk_mul_f32 v[150:151], v[4:5], v[146:147] op_sel_hi:[1,0]
	v_pk_mul_f32 v[152:153], v[6:7], v[146:147] op_sel_hi:[1,0]
	v_cvt_pk_bf16_f32 v150, v150, v151
	v_cvt_pk_bf16_f32 v151, v152, v153
	global_store_dwordx2 v[148:149], v[150:151], off offset:512
	v_pk_mul_f32 v[150:151], v[8:9], v[146:147] op_sel_hi:[1,0]
	v_pk_mul_f32 v[152:153], v[10:11], v[146:147] op_sel_hi:[1,0]
	v_cvt_pk_bf16_f32 v150, v150, v151
	v_cvt_pk_bf16_f32 v151, v152, v153
	global_store_dwordx2 v[148:149], v[150:151], off offset:1024
	v_pk_mul_f32 v[150:151], v[12:13], v[146:147] op_sel_hi:[1,0]
	v_pk_mul_f32 v[146:147], v[14:15], v[146:147] op_sel_hi:[1,0]
	s_add_i32 s10, s13, s26
	v_cvt_pk_bf16_f32 v150, v150, v151
	v_cvt_pk_bf16_f32 v151, v146, v147
	s_cmp_gt_i32 s10, 0x3fff
	global_store_dwordx2 v[148:149], v[150:151], off offset:1536
	s_cbranch_scc1 .LBB0_33
; __device__ __forceinline__ unsigned cvt_pk_bf16(float lo, float hi) { const f32x2_t v = {lo, hi}; const bf16x2_t r = __builtin_convertvector(v, bf16x2_t); return __builtin_bit_cast(unsigned, r); }
; __device__ __forceinline__ void p0_proc4(bf16_t* XB, int m0, int NGW, int lane, const f32x4 (&v)[4][4]) {
;     ...
;     for (int u = 0; u < 4; ++u) { const int m = m0 + u * NGW; if (m >= T) break;
;         const float rstd = 1.0f / sqrtf(s[u] * (1.0f / 1024.0f) + NORM_EPS);
;         u32x2* o8 = (u32x2*)(XB + (size_t)m * 1024) + lane;
; #pragma unroll
;         for (int j = 0; j < 4; ++j) { u32x2 w; w.x = cvt_pk_bf16(v[u][j][0] * rstd, v[u][j][1] * rstd); w.y = cvt_pk_bf16(v[u][j][2] * rstd, v[u][j][3] * rstd); o8[64 * j] = w; } }
	s_waitcnt lgkmcnt(1)
	v_add_f32_e32 v144, v144, v145
	v_fmamk_f32 v144, v144, 0x3a800000, v131
	v_mul_f32_e32 v145, 0x4f800000, v144
	v_cmp_gt_f32_e32 vcc, s25, v144
	s_ashr_i32 s11, s10, 31
	s_nop 0
	v_cndmask_b32_e32 v144, v144, v145, vcc
	v_sqrt_f32_e32 v145, v144
	s_nop 0
	v_add_u32_e32 v146, -1, v145
	v_fma_f32 v148, -v146, v145, v144
	v_add_u32_e32 v147, 1, v145
	v_cmp_ge_f32_e64 s[0:1], 0, v148
	s_nop 1
	v_cndmask_b32_e64 v146, v145, v146, s[0:1]
	v_fma_f32 v145, -v147, v145, v144
	v_cmp_lt_f32_e64 s[0:1], 0, v145
	s_nop 1
	v_cndmask_b32_e64 v145, v146, v147, s[0:1]
	v_mul_f32_e32 v146, 0x37800000, v145
	v_cndmask_b32_e32 v145, v145, v146, vcc
	v_cmp_class_f32_e32 vcc, v144, v132
	s_nop 1
	v_cndmask_b32_e32 v144, v145, v144, vcc
	v_div_scale_f32 v145, s[0:1], v144, v144, 1.0
	v_rcp_f32_e32 v146, v145
	s_lshl_b64 s[0:1], s[10:11], 11
	s_add_i32 s10, s23, s26
	s_cmp_gt_i32 s10, 0x3fff
	v_fma_f32 v147, -v145, v146, 1.0
	v_fmac_f32_e32 v146, v147, v146
	v_div_scale_f32 v147, vcc, 1.0, v144, 1.0
	v_mul_f32_e32 v148, v147, v146
	v_fma_f32 v149, -v145, v148, v147
	v_fmac_f32_e32 v148, v149, v146
	v_fma_f32 v145, -v145, v148, v147
	v_div_fmas_f32 v145, v145, v146, v148
	v_div_fixup_f32 v144, v145, v144, 1.0
	v_pk_mul_f32 v[148:149], v[16:17], v[144:145] op_sel_hi:[1,0]
	v_pk_mul_f32 v[150:151], v[18:19], v[144:145] op_sel_hi:[1,0]
	v_lshl_add_u64 v[146:147], v[128:129], 0, s[0:1]
	v_cvt_pk_bf16_f32 v148, v148, v149
	v_cvt_pk_bf16_f32 v149, v150, v151
	global_store_dwordx2 v[146:147], v[148:149], off
	v_pk_mul_f32 v[148:149], v[20:21], v[144:145] op_sel_hi:[1,0]
	v_pk_mul_f32 v[150:151], v[22:23], v[144:145] op_sel_hi:[1,0]
	v_cvt_pk_bf16_f32 v148, v148, v149
	v_cvt_pk_bf16_f32 v149, v150, v151
	global_store_dwordx2 v[146:147], v[148:149], off offset:512
	v_pk_mul_f32 v[148:149], v[24:25], v[144:145] op_sel_hi:[1,0]
	v_pk_mul_f32 v[150:151], v[26:27], v[144:145] op_sel_hi:[1,0]
	v_cvt_pk_bf16_f32 v148, v148, v149
	v_cvt_pk_bf16_f32 v149, v150, v151
	global_store_dwordx2 v[146:147], v[148:149], off offset:1024
	v_pk_mul_f32 v[148:149], v[28:29], v[144:145] op_sel_hi:[1,0]
	v_pk_mul_f32 v[144:145], v[30:31], v[144:145] op_sel_hi:[1,0]
	v_cvt_pk_bf16_f32 v148, v148, v149
	v_cvt_pk_bf16_f32 v149, v144, v145
	global_store_dwordx2 v[146:147], v[148:149], off offset:1536
	s_cbranch_scc1 .LBB0_33
	v_add_f32_e32 v142, v142, v143
	v_fmamk_f32 v142, v142, 0x3a800000, v131
	v_mul_f32_e32 v143, 0x4f800000, v142
	v_cmp_gt_f32_e32 vcc, s25, v142
	s_ashr_i32 s11, s10, 31
	s_nop 0
	v_cndmask_b32_e32 v142, v142, v143, vcc
	v_sqrt_f32_e32 v143, v142
	s_nop 0
	v_add_u32_e32 v144, -1, v143
	v_fma_f32 v146, -v144, v143, v142
	v_add_u32_e32 v145, 1, v143
	v_cmp_ge_f32_e64 s[0:1], 0, v146
	s_nop 1
	v_cndmask_b32_e64 v144, v143, v144, s[0:1]
	v_fma_f32 v143, -v145, v143, v142
	v_cmp_lt_f32_e64 s[0:1], 0, v143
	s_nop 1
	v_cndmask_b32_e64 v143, v144, v145, s[0:1]
	v_mul_f32_e32 v144, 0x37800000, v143
	v_cndmask_b32_e32 v143, v143, v144, vcc
	v_cmp_class_f32_e32 vcc, v142, v132
	s_nop 1
	v_cndmask_b32_e32 v142, v143, v142, vcc
	v_div_scale_f32 v143, s[0:1], v142, v142, 1.0
	v_rcp_f32_e32 v144, v143
	s_lshl_b64 s[0:1], s[10:11], 11
	s_add_i32 s10, s24, s26
	s_cmp_gt_i32 s10, 0x3fff
	v_fma_f32 v145, -v143, v144, 1.0
	v_fmac_f32_e32 v144, v145, v144
	v_div_scale_f32 v145, vcc, 1.0, v142, 1.0
	v_mul_f32_e32 v146, v145, v144
	v_fma_f32 v147, -v143, v146, v145
	v_fmac_f32_e32 v146, v147, v144
	v_fma_f32 v143, -v143, v146, v145
	v_div_fmas_f32 v143, v143, v144, v146
	v_div_fixup_f32 v142, v143, v142, 1.0
	v_pk_mul_f32 v[146:147], v[32:33], v[142:143] op_sel_hi:[1,0]
	v_pk_mul_f32 v[148:149], v[34:35], v[142:143] op_sel_hi:[1,0]
	v_lshl_add_u64 v[144:145], v[128:129], 0, s[0:1]
	v_cvt_pk_bf16_f32 v146, v146, v147
	v_cvt_pk_bf16_f32 v147, v148, v149
	global_store_dwordx2 v[144:145], v[146:147], off
	v_pk_mul_f32 v[146:147], v[36:37], v[142:143] op_sel_hi:[1,0]
	v_pk_mul_f32 v[148:149], v[38:39], v[142:143] op_sel_hi:[1,0]
	v_cvt_pk_bf16_f32 v146, v146, v147
	v_cvt_pk_bf16_f32 v147, v148, v149
	global_store_dwordx2 v[144:145], v[146:147], off offset:512
	v_pk_mul_f32 v[146:147], v[40:41], v[142:143] op_sel_hi:[1,0]
	v_pk_mul_f32 v[148:149], v[42:43], v[142:143] op_sel_hi:[1,0]
	v_cvt_pk_bf16_f32 v146, v146, v147
	v_cvt_pk_bf16_f32 v147, v148, v149
	global_store_dwordx2 v[144:145], v[146:147], off offset:1024
	v_pk_mul_f32 v[146:147], v[44:45], v[142:143] op_sel_hi:[1,0]
	v_pk_mul_f32 v[142:143], v[46:47], v[142:143] op_sel_hi:[1,0]
	v_cvt_pk_bf16_f32 v146, v146, v147
	v_cvt_pk_bf16_f32 v147, v142, v143
	global_store_dwordx2 v[144:145], v[146:147], off offset:1536
	s_cbranch_scc1 .LBB0_33
	s_waitcnt lgkmcnt(0)
	v_add_f32_e32 v140, v140, v141
	v_fmamk_f32 v140, v140, 0x3a800000, v131
	v_mul_f32_e32 v141, 0x4f800000, v140
	v_cmp_gt_f32_e32 vcc, s25, v140
	s_ashr_i32 s11, s10, 31
	s_nop 0
	v_cndmask_b32_e32 v140, v140, v141, vcc
	v_sqrt_f32_e32 v141, v140
	s_nop 0
	v_add_u32_e32 v142, -1, v141
	v_fma_f32 v144, -v142, v141, v140
	v_add_u32_e32 v143, 1, v141
	v_cmp_ge_f32_e64 s[0:1], 0, v144
	s_nop 1
	v_cndmask_b32_e64 v142, v141, v142, s[0:1]
	v_fma_f32 v141, -v143, v141, v140
	v_cmp_lt_f32_e64 s[0:1], 0, v141
	s_nop 1
	v_cndmask_b32_e64 v141, v142, v143, s[0:1]
	v_mul_f32_e32 v142, 0x37800000, v141
	v_cndmask_b32_e32 v141, v141, v142, vcc
	v_cmp_class_f32_e32 vcc, v140, v132
	s_nop 1
	v_cndmask_b32_e32 v140, v141, v140, vcc
	v_div_scale_f32 v141, s[0:1], v140, v140, 1.0
	v_rcp_f32_e32 v142, v141
	s_lshl_b64 s[0:1], s[10:11], 11
	v_fma_f32 v143, -v141, v142, 1.0
	v_fmac_f32_e32 v142, v143, v142
	v_div_scale_f32 v143, vcc, 1.0, v140, 1.0
	v_mul_f32_e32 v144, v143, v142
	v_fma_f32 v145, -v141, v144, v143
	v_fmac_f32_e32 v144, v145, v142
	v_fma_f32 v141, -v141, v144, v143
	v_div_fmas_f32 v141, v141, v142, v144
	v_div_fixup_f32 v140, v141, v140, 1.0
	v_pk_mul_f32 v[144:145], v[48:49], v[140:141] op_sel_hi:[1,0]
	v_pk_mul_f32 v[146:147], v[50:51], v[140:141] op_sel_hi:[1,0]
	v_lshl_add_u64 v[142:143], v[128:129], 0, s[0:1]
	v_cvt_pk_bf16_f32 v144, v144, v145
	v_cvt_pk_bf16_f32 v145, v146, v147
	global_store_dwordx2 v[142:143], v[144:145], off
	v_pk_mul_f32 v[144:145], v[52:53], v[140:141] op_sel_hi:[1,0]
	v_pk_mul_f32 v[146:147], v[54:55], v[140:141] op_sel_hi:[1,0]
	v_cvt_pk_bf16_f32 v144, v144, v145
	v_cvt_pk_bf16_f32 v145, v146, v147
	global_store_dwordx2 v[142:143], v[144:145], off offset:512
	v_pk_mul_f32 v[144:145], v[56:57], v[140:141] op_sel_hi:[1,0]
	v_pk_mul_f32 v[146:147], v[58:59], v[140:141] op_sel_hi:[1,0]
	v_cvt_pk_bf16_f32 v144, v144, v145
	v_cvt_pk_bf16_f32 v145, v146, v147
	global_store_dwordx2 v[142:143], v[144:145], off offset:1024
	v_pk_mul_f32 v[144:145], v[60:61], v[140:141] op_sel_hi:[1,0]
	v_pk_mul_f32 v[140:141], v[62:63], v[140:141] op_sel_hi:[1,0]
	v_cvt_pk_bf16_f32 v144, v144, v145
	v_cvt_pk_bf16_f32 v145, v140, v141
	global_store_dwordx2 v[142:143], v[144:145], off offset:1536
; __device__ __forceinline__ void p0_proc4(bf16_t* XB, int m0, int NGW, int lane, const f32x4 (&v)[4][4]) {
;     float s[4];
; #pragma unroll
;     for (int u = 0; u < 4; ++u) { float t = 0.f;
; #pragma unroll
;         for (int j = 0; j < 4; ++j) t += (v[u][j][0] * v[u][j][0] + v[u][j][1] * v[u][j][1]) + (v[u][j][2] * v[u][j][2] + v[u][j][3] * v[u][j][3]);
;         s[u] = t; }
; #pragma unroll
;     for (int o = 1; o < 64; o <<= 1) {
; #pragma unroll
;         for (int u = 0; u < 4; ++u) s[u] += __shfl_xor(s[u], o); }
; __device__ __forceinline__ void p0_prologue(const Args& a, LAS unsigned char* lds, int wave, int lane) {
;     ...
;             const int m2 = m1 + 4 * NGW; const bool has2 = m2 < T;
;             if (has2) p0_load4(a, m2, NGW, lane, va);
;             p0_proc4(XB, m1, NGW, lane, vb);
.LBB0_33:
	s_andn2_b64 vcc, exec, s[8:9]
	s_mov_b64 s[0:1], -1
	s_cbranch_vccnz .LBB0_25
	s_add_i32 s1, s16, s26
	s_add_i32 s0, s1, -6
	s_cmp_gt_i32 s0, 0x3fff
	s_cbranch_scc1 .LBB0_36
	s_add_i32 s7, s1, 0xffff7ffa
	s_ashr_i32 s1, s0, 31
	s_cmp_lt_i32 s0, 0x8000
	s_cselect_b32 s1, s1, 0
	s_cselect_b32 s0, s0, s7
	s_cselect_b32 s7, s77, s79
	s_cselect_b32 s8, s76, s78
	s_lshl_b64 s[0:1], s[0:1], 12
	s_add_u32 s0, s8, s0
	s_addc_u32 s1, s7, s1
	global_load_dwordx4 v[0:3], v130, s[0:1]
	global_load_dwordx4 v[4:7], v130, s[0:1] offset:1024
	global_load_dwordx4 v[8:11], v130, s[0:1] offset:2048
	global_load_dwordx4 v[12:15], v130, s[0:1] offset:3072
	s_add_i32 s0, s17, s26
	s_min_i32 s7, s0, 0x3fff
	s_ashr_i32 s1, s7, 31
	s_add_i32 s8, s7, 0xffff8000
	s_cmp_lt_i32 s0, 0x8000
	s_cselect_b32 s1, s1, 0
	s_cselect_b32 s0, s7, s8
	s_cselect_b32 s7, s77, s79
	s_cselect_b32 s8, s76, s78
	s_lshl_b64 s[0:1], s[0:1], 12
	s_add_u32 s0, s8, s0
	s_addc_u32 s1, s7, s1
	global_load_dwordx4 v[16:19], v130, s[0:1]
	global_load_dwordx4 v[20:23], v130, s[0:1] offset:1024
	global_load_dwordx4 v[24:27], v130, s[0:1] offset:2048
	global_load_dwordx4 v[28:31], v130, s[0:1] offset:3072
	s_add_i32 s0, s18, s26
	s_min_i32 s7, s0, 0x3fff
	s_ashr_i32 s1, s7, 31
	s_add_i32 s8, s7, 0xffff8000
	s_cmp_lt_i32 s0, 0x8000
	s_cselect_b32 s1, s1, 0
	s_cselect_b32 s0, s7, s8
	s_cselect_b32 s7, s77, s79
	s_cselect_b32 s8, s76, s78
	s_lshl_b64 s[0:1], s[0:1], 12
	s_add_u32 s0, s8, s0
	s_addc_u32 s1, s7, s1
	global_load_dwordx4 v[32:35], v130, s[0:1]
	global_load_dwordx4 v[36:39], v130, s[0:1] offset:1024
	global_load_dwordx4 v[40:43], v130, s[0:1] offset:2048
	global_load_dwordx4 v[44:47], v130, s[0:1] offset:3072
	s_add_i32 s0, s19, s26
	s_min_i32 s7, s0, 0x3fff
	s_ashr_i32 s1, s7, 31
	s_add_i32 s8, s7, 0xffff8000
	s_cmp_lt_i32 s0, 0x8000
	s_cselect_b32 s1, s1, 0
	s_cselect_b32 s0, s7, s8
	s_cselect_b32 s7, s77, s79
	s_cselect_b32 s8, s76, s78
	s_lshl_b64 s[0:1], s[0:1], 12
	s_add_u32 s0, s8, s0
	s_addc_u32 s1, s7, s1
	global_load_dwordx4 v[48:51], v130, s[0:1]
	global_load_dwordx4 v[52:55], v130, s[0:1] offset:1024
	global_load_dwordx4 v[56:59], v130, s[0:1] offset:2048
	global_load_dwordx4 v[60:63], v130, s[0:1] offset:3072
.LBB0_36:
	s_waitcnt lgkmcnt(0)
	v_pk_mul_f32 v[140:141], v[78:79], v[78:79]
	v_pk_mul_f32 v[142:143], v[76:77], v[76:77]
	s_ashr_i32 s7, s6, 31
	v_pk_mov_b32 v[144:145], v[142:143], v[140:141] op_sel:[1,0]
	v_mov_b32_e32 v143, v141
	v_pk_add_f32 v[140:141], v[144:145], v[142:143]
	v_pk_mul_f32 v[142:143], v[74:75], v[74:75]
	v_pk_add_f32 v[140:141], v[140:141], v[140:141] op_sel_hi:[0,1]
	v_pk_mul_f32 v[144:145], v[72:73], v[72:73]
	v_mul_f32_e32 v140, v68, v68
	v_pk_mov_b32 v[146:147], v[144:145], v[142:143] op_sel:[1,0]
	v_mov_b32_e32 v145, v143
	v_pk_add_f32 v[142:143], v[146:147], v[144:145]
	v_pk_fma_f32 v[144:145], v[68:69], v[68:69], v[140:141] op_sel_hi:[1,1,0]
	v_mul_f32_e32 v140, v70, v70
	v_pk_add_f32 v[142:143], v[142:143], v[142:143] op_sel_hi:[0,1]
	v_pk_fma_f32 v[146:147], v[70:71], v[70:71], v[140:141] op_sel_hi:[1,1,0]
	v_mul_f32_e32 v144, v64, v64
	v_mul_f32_e32 v146, v65, v65
	v_mul_f32_e32 v142, v66, v66
	v_mul_f32_e32 v140, v67, v67
	v_pk_add_f32 v[144:145], v[144:145], v[146:147]
	v_pk_add_f32 v[140:141], v[142:143], v[140:141]
	v_mul_f32_e32 v142, v95, v95
	v_pk_add_f32 v[140:141], v[144:145], v[140:141]
	v_fmac_f32_e32 v142, v94, v94
	v_add_f32_e32 v140, v140, v141
	v_mul_f32_e32 v141, v93, v93
	v_fmac_f32_e32 v141, v92, v92
	v_add_f32_e32 v141, v141, v142
	v_mul_f32_e32 v142, v89, v89
	v_mul_f32_e32 v143, v91, v91
	v_fmac_f32_e32 v142, v88, v88
	v_fmac_f32_e32 v143, v90, v90
	v_add_f32_e32 v142, v142, v143
	v_add_f32_e32 v141, v142, v141
	v_mul_f32_e32 v142, v85, v85
	v_mul_f32_e32 v143, v87, v87
	v_fmac_f32_e32 v142, v84, v84
	v_fmac_f32_e32 v143, v86, v86
	v_add_f32_e32 v142, v142, v143
	v_add_f32_e32 v141, v142, v141
	v_mul_f32_e32 v142, v81, v81
	v_mul_f32_e32 v143, v83, v83
	v_fmac_f32_e32 v142, v80, v80
	v_fmac_f32_e32 v143, v82, v82
	v_add_f32_e32 v142, v142, v143
	v_add_f32_e32 v141, v142, v141
	v_mul_f32_e32 v142, v109, v109
	v_mul_f32_e32 v143, v111, v111
	v_fmac_f32_e32 v142, v108, v108
	v_fmac_f32_e32 v143, v110, v110
	v_add_f32_e32 v142, v142, v143
	v_mul_f32_e32 v143, v105, v105
	v_mul_f32_e32 v144, v107, v107
	v_fmac_f32_e32 v143, v104, v104
	v_fmac_f32_e32 v144, v106, v106
	v_add_f32_e32 v143, v143, v144
	v_add_f32_e32 v142, v143, v142
	v_mul_f32_e32 v143, v101, v101
	v_mul_f32_e32 v144, v103, v103
	v_fmac_f32_e32 v143, v100, v100
	v_fmac_f32_e32 v144, v102, v102
	v_add_f32_e32 v143, v143, v144
	v_add_f32_e32 v142, v143, v142
	v_mul_f32_e32 v143, v97, v97
	v_mul_f32_e32 v144, v99, v99
	v_fmac_f32_e32 v143, v96, v96
	v_fmac_f32_e32 v144, v98, v98
	v_add_f32_e32 v143, v143, v144
	v_add_f32_e32 v142, v143, v142
	v_mul_f32_e32 v143, v125, v125
	v_mul_f32_e32 v144, v127, v127
	v_fmac_f32_e32 v143, v124, v124
	v_fmac_f32_e32 v144, v126, v126
	v_add_f32_e32 v143, v143, v144
	v_mul_f32_e32 v144, v121, v121
	v_mul_f32_e32 v145, v123, v123
	v_fmac_f32_e32 v144, v120, v120
	v_fmac_f32_e32 v145, v122, v122
	v_add_f32_e32 v144, v144, v145
	v_add_f32_e32 v143, v144, v143
	v_mul_f32_e32 v144, v117, v117
	v_mul_f32_e32 v145, v119, v119
	ds_bpermute_b32 v146, v135, v140
	v_fmac_f32_e32 v144, v116, v116
	v_fmac_f32_e32 v145, v118, v118
	v_add_f32_e32 v144, v144, v145
	v_add_f32_e32 v143, v144, v143
	v_mul_f32_e32 v144, v113, v113
	v_mul_f32_e32 v145, v115, v115
	v_fmac_f32_e32 v144, v112, v112
	v_fmac_f32_e32 v145, v114, v114
	v_add_f32_e32 v144, v144, v145
	s_waitcnt lgkmcnt(0)
; __device__ __forceinline__ unsigned cvt_pk_bf16(float lo, float hi) { const f32x2_t v = {lo, hi}; const bf16x2_t r = __builtin_convertvector(v, bf16x2_t); return __builtin_bit_cast(unsigned, r); }
; __device__ __forceinline__ void p0_proc4(bf16_t* XB, int m0, int NGW, int lane, const f32x4 (&v)[4][4]) {
;     ...
; #pragma unroll
;     for (int o = 1; o < 64; o <<= 1) {
; #pragma unroll
;         for (int u = 0; u < 4; ++u) s[u] += __shfl_xor(s[u], o); }
; #pragma unroll
;     for (int u = 0; u < 4; ++u) { const int m = m0 + u * NGW; if (m >= T) break;
;         const float rstd = 1.0f / sqrtf(s[u] * (1.0f / 1024.0f) + NORM_EPS);
;         u32x2* o8 = (u32x2*)(XB + (size_t)m * 1024) + lane;
; #pragma unroll
;         for (int j = 0; j < 4; ++j) { u32x2 w; w.x = cvt_pk_bf16(v[u][j][0] * rstd, v[u][j][1] * rstd); w.y = cvt_pk_bf16(v[u][j][2] * rstd, v[u][j][3] * rstd); o8[64 * j] = w; } }
; __device__ __forceinline__ void p0_prologue(const Args& a, LAS unsigned char* lds, int wave, int lane) {
;     ...
;             p0_proc4(XB, m1, NGW, lane, vb);
;             if (!has2) break;
	v_add_f32_e32 v140, v140, v146
	v_add_f32_e32 v143, v144, v143
	ds_bpermute_b32 v145, v136, v140
	ds_bpermute_b32 v147, v135, v141
	ds_bpermute_b32 v144, v135, v142
	ds_bpermute_b32 v135, v135, v143
	s_waitcnt lgkmcnt(3)
	v_add_f32_e32 v140, v140, v145
	s_waitcnt lgkmcnt(2)
	v_add_f32_e32 v141, v141, v147
	ds_bpermute_b32 v146, v136, v141
	s_waitcnt lgkmcnt(1)
	v_add_f32_e32 v135, v143, v135
	ds_bpermute_b32 v143, v137, v140
	v_add_f32_e32 v142, v142, v144
	ds_bpermute_b32 v144, v136, v142
	ds_bpermute_b32 v136, v136, v135
	s_waitcnt lgkmcnt(3)
	v_add_f32_e32 v141, v141, v146
	s_waitcnt lgkmcnt(2)
	v_add_f32_e32 v140, v140, v143
	ds_bpermute_b32 v143, v138, v140
	s_waitcnt lgkmcnt(2)
	v_add_f32_e32 v142, v142, v144
	ds_bpermute_b32 v144, v137, v141
	s_waitcnt lgkmcnt(2)
	v_add_f32_e32 v135, v135, v136
	ds_bpermute_b32 v145, v137, v142
	ds_bpermute_b32 v137, v137, v135
	s_waitcnt lgkmcnt(3)
	v_add_f32_e32 v140, v140, v143
	s_waitcnt lgkmcnt(2)
	v_add_f32_e32 v136, v141, v144
	ds_bpermute_b32 v144, v139, v140
	s_waitcnt lgkmcnt(2)
	v_add_f32_e32 v141, v142, v145
	s_waitcnt lgkmcnt(1)
	v_add_f32_e32 v135, v135, v137
	ds_bpermute_b32 v142, v138, v136
	ds_bpermute_b32 v143, v138, v141
	ds_bpermute_b32 v137, v138, v135
	s_waitcnt lgkmcnt(3)
	v_add_f32_e32 v138, v140, v144
	ds_bpermute_b32 v140, v134, v138
	s_waitcnt lgkmcnt(3)
	v_add_f32_e32 v136, v136, v142
	s_waitcnt lgkmcnt(2)
	v_add_f32_e32 v141, v141, v143
	s_waitcnt lgkmcnt(1)
	v_add_f32_e32 v135, v135, v137
	ds_bpermute_b32 v137, v139, v136
	s_waitcnt lgkmcnt(1)
	v_add_f32_e32 v138, v138, v140
	v_fmamk_f32 v138, v138, 0x3a800000, v131
	v_mul_f32_e32 v140, 0x4f800000, v138
	v_cmp_gt_f32_e32 vcc, s25, v138
	ds_bpermute_b32 v142, v139, v141
	ds_bpermute_b32 v139, v139, v135
	v_cndmask_b32_e32 v140, v138, v140, vcc
	v_sqrt_f32_e32 v143, v140
	s_waitcnt lgkmcnt(2)
	v_add_f32_e32 v138, v136, v137
	s_waitcnt lgkmcnt(1)
	v_add_f32_e32 v136, v141, v142
	s_waitcnt lgkmcnt(0)
	v_add_f32_e32 v135, v135, v139
	v_add_u32_e32 v137, -1, v143
	v_fma_f32 v139, -v137, v143, v140
	v_cmp_ge_f32_e64 s[0:1], 0, v139
	v_add_u32_e32 v139, 1, v143
	v_fma_f32 v141, -v139, v143, v140
	v_cndmask_b32_e64 v137, v143, v137, s[0:1]
	v_cmp_lt_f32_e64 s[0:1], 0, v141
	s_nop 1
	v_cndmask_b32_e64 v137, v137, v139, s[0:1]
	v_mul_f32_e32 v139, 0x37800000, v137
	v_cndmask_b32_e32 v137, v137, v139, vcc
	v_cmp_class_f32_e32 vcc, v140, v132
	ds_bpermute_b32 v139, v134, v138
	s_nop 0
	v_cndmask_b32_e32 v140, v137, v140, vcc
	v_div_scale_f32 v141, s[0:1], v140, v140, 1.0
	v_rcp_f32_e32 v142, v141
	s_lshl_b64 s[0:1], s[6:7], 11
	ds_bpermute_b32 v137, v134, v136
	ds_bpermute_b32 v134, v134, v135
	v_fma_f32 v143, -v141, v142, 1.0
	v_fmac_f32_e32 v142, v143, v142
	v_div_scale_f32 v143, vcc, 1.0, v140, 1.0
	v_mul_f32_e32 v144, v143, v142
	v_fma_f32 v145, -v141, v144, v143
	v_fmac_f32_e32 v144, v145, v142
	v_fma_f32 v141, -v141, v144, v143
	v_div_fmas_f32 v141, v141, v142, v144
	v_div_fixup_f32 v140, v141, v140, 1.0
	v_pk_mul_f32 v[144:145], v[76:77], v[140:141] op_sel_hi:[1,0]
	v_pk_mul_f32 v[146:147], v[78:79], v[140:141] op_sel_hi:[1,0]
	v_lshl_add_u64 v[142:143], v[128:129], 0, s[0:1]
	v_cvt_pk_bf16_f32 v144, v144, v145
	v_cvt_pk_bf16_f32 v145, v146, v147
	global_store_dwordx2 v[142:143], v[144:145], off
	v_pk_mul_f32 v[144:145], v[72:73], v[140:141] op_sel_hi:[1,0]
	v_pk_mul_f32 v[146:147], v[74:75], v[140:141] op_sel_hi:[1,0]
	v_cvt_pk_bf16_f32 v144, v144, v145
	v_cvt_pk_bf16_f32 v145, v146, v147
	global_store_dwordx2 v[142:143], v[144:145], off offset:512
	v_pk_mul_f32 v[144:145], v[68:69], v[140:141] op_sel_hi:[1,0]
	v_pk_mul_f32 v[146:147], v[70:71], v[140:141] op_sel_hi:[1,0]
	v_cvt_pk_bf16_f32 v144, v144, v145
	v_cvt_pk_bf16_f32 v145, v146, v147
	global_store_dwordx2 v[142:143], v[144:145], off offset:1024
	v_pk_mul_f32 v[144:145], v[64:65], v[140:141] op_sel_hi:[1,0]
	v_pk_mul_f32 v[140:141], v[66:67], v[140:141] op_sel_hi:[1,0]
	s_add_i32 s6, s15, s26
	v_cvt_pk_bf16_f32 v144, v144, v145
	v_cvt_pk_bf16_f32 v145, v140, v141
	s_cmp_gt_i32 s6, 0x3fff
	global_store_dwordx2 v[142:143], v[144:145], off offset:1536
	s_cbranch_scc1 .LBB0_24
	s_waitcnt lgkmcnt(2)
	v_add_f32_e32 v138, v138, v139
	v_fmamk_f32 v138, v138, 0x3a800000, v131
	v_mul_f32_e32 v139, 0x4f800000, v138
	v_cmp_gt_f32_e32 vcc, s25, v138
	s_ashr_i32 s7, s6, 31
	s_nop 0
	v_cndmask_b32_e32 v138, v138, v139, vcc
	v_sqrt_f32_e32 v139, v138
	s_nop 0
	v_add_u32_e32 v140, -1, v139
	v_fma_f32 v142, -v140, v139, v138
	v_add_u32_e32 v141, 1, v139
	v_cmp_ge_f32_e64 s[0:1], 0, v142
	s_nop 1
	v_cndmask_b32_e64 v140, v139, v140, s[0:1]
	v_fma_f32 v139, -v141, v139, v138
	v_cmp_lt_f32_e64 s[0:1], 0, v139
	s_nop 1
	v_cndmask_b32_e64 v139, v140, v141, s[0:1]
	v_mul_f32_e32 v140, 0x37800000, v139
	v_cndmask_b32_e32 v139, v139, v140, vcc
	v_cmp_class_f32_e32 vcc, v138, v132
	s_nop 1
	v_cndmask_b32_e32 v138, v139, v138, vcc
	v_div_scale_f32 v139, s[0:1], v138, v138, 1.0
	v_rcp_f32_e32 v140, v139
	s_lshl_b64 s[0:1], s[6:7], 11
	s_add_i32 s6, s21, s26
	s_cmp_gt_i32 s6, 0x3fff
	v_fma_f32 v141, -v139, v140, 1.0
	v_fmac_f32_e32 v140, v141, v140
	v_div_scale_f32 v141, vcc, 1.0, v138, 1.0
	v_mul_f32_e32 v142, v141, v140
	v_fma_f32 v143, -v139, v142, v141
	v_fmac_f32_e32 v142, v143, v140
	v_fma_f32 v139, -v139, v142, v141
	v_div_fmas_f32 v139, v139, v140, v142
	v_div_fixup_f32 v138, v139, v138, 1.0
	v_pk_mul_f32 v[142:143], v[92:93], v[138:139] op_sel_hi:[1,0]
	v_pk_mul_f32 v[144:145], v[94:95], v[138:139] op_sel_hi:[1,0]
	v_lshl_add_u64 v[140:141], v[128:129], 0, s[0:1]
	v_cvt_pk_bf16_f32 v142, v142, v143
	v_cvt_pk_bf16_f32 v143, v144, v145
	global_store_dwordx2 v[140:141], v[142:143], off
	v_pk_mul_f32 v[142:143], v[88:89], v[138:139] op_sel_hi:[1,0]
	v_pk_mul_f32 v[144:145], v[90:91], v[138:139] op_sel_hi:[1,0]
	v_cvt_pk_bf16_f32 v142, v142, v143
	v_cvt_pk_bf16_f32 v143, v144, v145
	global_store_dwordx2 v[140:141], v[142:143], off offset:512
	v_pk_mul_f32 v[142:143], v[84:85], v[138:139] op_sel_hi:[1,0]
	v_pk_mul_f32 v[144:145], v[86:87], v[138:139] op_sel_hi:[1,0]
	v_cvt_pk_bf16_f32 v142, v142, v143
	v_cvt_pk_bf16_f32 v143, v144, v145
	global_store_dwordx2 v[140:141], v[142:143], off offset:1024
	v_pk_mul_f32 v[142:143], v[80:81], v[138:139] op_sel_hi:[1,0]
	v_pk_mul_f32 v[138:139], v[82:83], v[138:139] op_sel_hi:[1,0]
	v_cvt_pk_bf16_f32 v142, v142, v143
	v_cvt_pk_bf16_f32 v143, v138, v139
	global_store_dwordx2 v[140:141], v[142:143], off offset:1536
	s_cbranch_scc1 .LBB0_24
; __device__ __forceinline__ unsigned cvt_pk_bf16(float lo, float hi) { const f32x2_t v = {lo, hi}; const bf16x2_t r = __builtin_convertvector(v, bf16x2_t); return __builtin_bit_cast(unsigned, r); }
; __device__ __forceinline__ void p0_proc4(bf16_t* XB, int m0, int NGW, int lane, const f32x4 (&v)[4][4]) {
;     ...
;     for (int u = 0; u < 4; ++u) { const int m = m0 + u * NGW; if (m >= T) break;
;         const float rstd = 1.0f / sqrtf(s[u] * (1.0f / 1024.0f) + NORM_EPS);
;         u32x2* o8 = (u32x2*)(XB + (size_t)m * 1024) + lane;
; #pragma unroll
;         for (int j = 0; j < 4; ++j) { u32x2 w; w.x = cvt_pk_bf16(v[u][j][0] * rstd, v[u][j][1] * rstd); w.y = cvt_pk_bf16(v[u][j][2] * rstd, v[u][j][3] * rstd); o8[64 * j] = w; } }
	s_waitcnt lgkmcnt(1)
	v_add_f32_e32 v136, v136, v137
	v_fmamk_f32 v136, v136, 0x3a800000, v131
	v_mul_f32_e32 v137, 0x4f800000, v136
	v_cmp_gt_f32_e32 vcc, s25, v136
	s_ashr_i32 s7, s6, 31
	s_nop 0
	v_cndmask_b32_e32 v136, v136, v137, vcc
	v_sqrt_f32_e32 v137, v136
	s_nop 0
	v_add_u32_e32 v138, -1, v137
	v_fma_f32 v140, -v138, v137, v136
	v_add_u32_e32 v139, 1, v137
	v_cmp_ge_f32_e64 s[0:1], 0, v140
	s_nop 1
	v_cndmask_b32_e64 v138, v137, v138, s[0:1]
	v_fma_f32 v137, -v139, v137, v136
	v_cmp_lt_f32_e64 s[0:1], 0, v137
	s_nop 1
	v_cndmask_b32_e64 v137, v138, v139, s[0:1]
	v_mul_f32_e32 v138, 0x37800000, v137
	v_cndmask_b32_e32 v137, v137, v138, vcc
	v_cmp_class_f32_e32 vcc, v136, v132
	s_nop 1
	v_cndmask_b32_e32 v136, v137, v136, vcc
	v_div_scale_f32 v137, s[0:1], v136, v136, 1.0
	v_rcp_f32_e32 v138, v137
	s_lshl_b64 s[0:1], s[6:7], 11
	s_add_i32 s6, s22, s26
	s_cmp_gt_i32 s6, 0x3fff
	v_fma_f32 v139, -v137, v138, 1.0
	v_fmac_f32_e32 v138, v139, v138
	v_div_scale_f32 v139, vcc, 1.0, v136, 1.0
	v_mul_f32_e32 v140, v139, v138
	v_fma_f32 v141, -v137, v140, v139
	v_fmac_f32_e32 v140, v141, v138
	v_fma_f32 v137, -v137, v140, v139
	v_div_fmas_f32 v137, v137, v138, v140
	v_div_fixup_f32 v136, v137, v136, 1.0
	v_pk_mul_f32 v[140:141], v[108:109], v[136:137] op_sel_hi:[1,0]
	v_pk_mul_f32 v[142:143], v[110:111], v[136:137] op_sel_hi:[1,0]
	v_lshl_add_u64 v[138:139], v[128:129], 0, s[0:1]
	v_cvt_pk_bf16_f32 v140, v140, v141
	v_cvt_pk_bf16_f32 v141, v142, v143
	global_store_dwordx2 v[138:139], v[140:141], off
	v_pk_mul_f32 v[140:141], v[104:105], v[136:137] op_sel_hi:[1,0]
	v_pk_mul_f32 v[142:143], v[106:107], v[136:137] op_sel_hi:[1,0]
	v_cvt_pk_bf16_f32 v140, v140, v141
	v_cvt_pk_bf16_f32 v141, v142, v143
	global_store_dwordx2 v[138:139], v[140:141], off offset:512
	v_pk_mul_f32 v[140:141], v[100:101], v[136:137] op_sel_hi:[1,0]
	v_pk_mul_f32 v[142:143], v[102:103], v[136:137] op_sel_hi:[1,0]
	v_cvt_pk_bf16_f32 v140, v140, v141
	v_cvt_pk_bf16_f32 v141, v142, v143
	global_store_dwordx2 v[138:139], v[140:141], off offset:1024
	v_pk_mul_f32 v[140:141], v[96:97], v[136:137] op_sel_hi:[1,0]
	v_pk_mul_f32 v[136:137], v[98:99], v[136:137] op_sel_hi:[1,0]
	v_cvt_pk_bf16_f32 v140, v140, v141
	v_cvt_pk_bf16_f32 v141, v136, v137
	global_store_dwordx2 v[138:139], v[140:141], off offset:1536
	s_cbranch_scc1 .LBB0_24
	s_waitcnt lgkmcnt(0)
	v_add_f32_e32 v134, v135, v134
	v_fmamk_f32 v134, v134, 0x3a800000, v131
	v_mul_f32_e32 v135, 0x4f800000, v134
	v_cmp_gt_f32_e32 vcc, s25, v134
	s_ashr_i32 s7, s6, 31
	s_nop 0
	v_cndmask_b32_e32 v134, v134, v135, vcc
	v_sqrt_f32_e32 v135, v134
	s_nop 0
	v_add_u32_e32 v136, -1, v135
	v_fma_f32 v138, -v136, v135, v134
	v_add_u32_e32 v137, 1, v135
	v_cmp_ge_f32_e64 s[0:1], 0, v138
	s_nop 1
	v_cndmask_b32_e64 v136, v135, v136, s[0:1]
	v_fma_f32 v135, -v137, v135, v134
	v_cmp_lt_f32_e64 s[0:1], 0, v135
	s_nop 1
	v_cndmask_b32_e64 v135, v136, v137, s[0:1]
	v_mul_f32_e32 v136, 0x37800000, v135
	v_cndmask_b32_e32 v135, v135, v136, vcc
	v_cmp_class_f32_e32 vcc, v134, v132
	s_nop 1
	v_cndmask_b32_e32 v134, v135, v134, vcc
	v_div_scale_f32 v135, s[0:1], v134, v134, 1.0
	v_rcp_f32_e32 v136, v135
	s_lshl_b64 s[0:1], s[6:7], 11
	v_fma_f32 v137, -v135, v136, 1.0
	v_fmac_f32_e32 v136, v137, v136
	v_div_scale_f32 v137, vcc, 1.0, v134, 1.0
	v_mul_f32_e32 v138, v137, v136
	v_fma_f32 v139, -v135, v138, v137
	v_fmac_f32_e32 v138, v139, v136
	v_fma_f32 v135, -v135, v138, v137
	v_div_fmas_f32 v135, v135, v136, v138
	v_div_fixup_f32 v134, v135, v134, 1.0
	v_pk_mul_f32 v[138:139], v[124:125], v[134:135] op_sel_hi:[1,0]
	v_pk_mul_f32 v[140:141], v[126:127], v[134:135] op_sel_hi:[1,0]
	v_lshl_add_u64 v[136:137], v[128:129], 0, s[0:1]
	v_cvt_pk_bf16_f32 v138, v138, v139
	v_cvt_pk_bf16_f32 v139, v140, v141
	global_store_dwordx2 v[136:137], v[138:139], off
	v_pk_mul_f32 v[138:139], v[120:121], v[134:135] op_sel_hi:[1,0]
	v_pk_mul_f32 v[140:141], v[122:123], v[134:135] op_sel_hi:[1,0]
	v_cvt_pk_bf16_f32 v138, v138, v139
	v_cvt_pk_bf16_f32 v139, v140, v141
	global_store_dwordx2 v[136:137], v[138:139], off offset:512
	v_pk_mul_f32 v[138:139], v[116:117], v[134:135] op_sel_hi:[1,0]
	v_pk_mul_f32 v[140:141], v[118:119], v[134:135] op_sel_hi:[1,0]
	v_cvt_pk_bf16_f32 v138, v138, v139
	v_cvt_pk_bf16_f32 v139, v140, v141
	global_store_dwordx2 v[136:137], v[138:139], off offset:1024
	v_pk_mul_f32 v[138:139], v[112:113], v[134:135] op_sel_hi:[1,0]
	v_pk_mul_f32 v[134:135], v[114:115], v[134:135] op_sel_hi:[1,0]
	v_cvt_pk_bf16_f32 v138, v138, v139
	v_cvt_pk_bf16_f32 v139, v134, v135
	global_store_dwordx2 v[136:137], v[138:139], off offset:1536
	s_branch .LBB0_24

;     __device__ bool next(int i, Unit& u) const {
;         const long L = (long)i * G + c; if (L >= nwg) return false;
;         int wgid = (int)L; { const int q = nwg / NXCD, r = nwg % NXCD, xcd = wgid % NXCD, off = wgid / NXCD; wgid = (xcd < r ? xcd * (q + 1) : r * (q + 1) + (xcd - r) * q) + off; }
;         const int nig = WGM * nN, gid = wgid / nig, fm = gid * WGM, gsz = (nM - fm) < WGM ? (nM - fm) : WGM;
;         u.pm = fm + ((wgid % nig) % gsz); u.pn = (wgid % nig) / gsz; return true;
; __global__ void __launch_bounds__(512, 2) fwd_kernel(Args a) {
;     ...
;         SchedA S; S.init(T, NIN, gridDim.x, blockIdx.x); S.XB = (const char*)(ws + WS_XB); S.W = (const char*)(ws + WS_WIN);
;         EpiA E; E.ws = ws; E.GA = (bf16_t*)a.out;
;         E.qn_a = a.in[4]; E.kn_a = a.in[5]; E.qn_b = a.in[7]; E.kn_b = a.in[8];
;         pg8::gemm_phase<EpiA, SchedA>(lds, S, E);
.LBB0_160:
	s_cmp_lt_i32 s66, 2
	s_cselect_b64 s[4:5], -1, 0
	s_and_b64 s[6:7], s[4:5], s[0:1]
	s_andn2_b64 vcc, exec, s[6:7]
	s_cbranch_vccnz .LBB0_212
	s_mov_b32 s99, -1
	s_cmpk_lt_i32 s2, 0xfc0
	s_cselect_b64 s[0:1], -1, 0
	s_cmpk_gt_i32 s2, 0xfbf
	v_readfirstlane_b32 s4, v190
	s_cbranch_scc1 .LBB0_163
	s_ashr_i32 s5, s2, 31
	s_lshr_b32 s5, s5, 29
	s_add_i32 s5, s2, s5
	s_ashr_i32 s8, s5, 3
	s_and_b32 s5, s5, -8
	s_sub_i32 s5, s2, s5
	s_cmp_lt_i32 s5, 0
	s_movk_i32 s9, 0x1f9
	s_cselect_b32 s9, s9, 0x1f8
	s_mul_i32 s5, s5, s9
	s_add_i32 s5, s5, s8
	s_mul_hi_i32 s8, s5, 0x30c30c31
	s_lshr_b32 s9, s8, 31
	s_ashr_i32 s8, s8, 4
	s_add_i32 s8, s8, s9
	s_lshl_b32 s9, s8, 2
	s_mulk_i32 s8, 0x54
	s_sub_i32 s5, s5, s8
	s_bfe_i32 s8, s5, 0x80000
	s_bfe_u32 s8, s8, 0x2000d
	s_add_i32 s8, s5, s8
	s_bfe_i32 s10, s8, 0x80000
	s_and_b32 s8, s8, 0xfc
	s_sub_i32 s5, s5, s8
	s_sext_i32_i16 s10, s10
	s_sext_i32_i8 s5, s5
	s_add_i32 s8, s9, s5
	s_ashr_i32 s38, s10, 2
	s_mul_i32 s100, s8, 0xaab
	s_lshr_b32 s100, s100, 16
	s_mul_i32 s101, s100, 24
	s_sub_i32 s101, s8, s101
	s_lshl_b32 s101, s101, 3
	s_or_b32 s8, s101, s100

;     __device__ bool next(int i, Unit& u) const {
;         const long L = (long)i * G + c; if (L >= nwg) return false;
;         int wgid = (int)L; { const int q = nwg / NXCD, r = nwg % NXCD, xcd = wgid % NXCD, off = wgid / NXCD; wgid = (xcd < r ? xcd * (q + 1) : r * (q + 1) + (xcd - r) * q) + off; }
;         const int nig = WGM * nN, gid = wgid / nig, fm = gid * WGM, gsz = (nM - fm) < WGM ? (nM - fm) : WGM;
;         u.pm = fm + ((wgid % nig) % gsz); u.pn = (wgid % nig) / gsz; return true;
; template <class Epi, class Sched>
; __device__ __forceinline__ void gemm_phase(LAS unsigned char* lds, const Sched& S, const Epi& E, bool natural = false) {
;     ...
;         const bool has_next = S.next(ui + 1, nxt);
;         const char* nA = cA; const char* nB = cB; if (has_next) S.ptrs(nxt, nA, nB);
;     __device__ __forceinline__ void ptrs(const Unit& u, const char*& cA, const char*& cB) const {
;         const char* x = XB + (size_t)u.pm * (256 * 1024 * 2); const char* w = W + (size_t)u.pn * (256 * 1024 * 2);
;         if (u.pn >= 19) { cA = w; cB = x; } else { cA = x; cB = w; }
;     }
.LBB0_169:
	s_add_i32 s70, s70, 1
	s_mul_i32 s0, s70, s56
	s_mul_hi_u32 s1, s70, s50
	s_add_i32 s1, s1, s0
	s_mul_i32 s0, s70, s50
	s_add_u32 s4, s0, s2
	s_addc_u32 s5, s1, s57
	s_cmp_lt_u32 s4, 0xfc0
	s_cselect_b64 s[0:1], -1, 0
	s_cselect_b64 vcc, 0, -1
	s_cbranch_vccnz .LBB0_171
	s_ashr_i32 s5, s4, 31
	s_lshr_b32 s5, s5, 29
	s_add_i32 s5, s4, s5
	s_ashr_i32 s30, s5, 3
	s_and_b32 s5, s5, -8
	s_sub_i32 s4, s4, s5
	s_cmp_lt_i32 s4, 0
	s_cselect_b32 s5, s58, 0x1f8
	s_mul_i32 s4, s4, s5
	s_add_i32 s4, s4, s30
	s_mul_hi_i32 s5, s4, 0x30c30c31
	s_lshr_b32 s30, s5, 31
	s_ashr_i32 s5, s5, 4
	s_add_i32 s5, s5, s30
	s_lshl_b32 s31, s5, 2
	s_sub_i32 s30, 0xc0, s31
	s_min_i32 s34, s30, 4
	s_abs_i32 s30, s34
	v_cvt_f32_u32_e32 v0, s30
	s_sub_i32 s36, 0, s30
	s_mulk_i32 s5, 0x54
	s_sub_i32 s4, s4, s5
	v_rcp_iflag_f32_e32 v0, v0
	s_abs_i32 s5, s4
	s_xor_b32 s35, s4, s34
	s_ashr_i32 s35, s35, 31
	v_mul_f32_e32 v0, 0x4f7ffffe, v0
	v_cvt_u32_f32_e32 v0, v0
	s_nop 0
	v_readfirstlane_b32 s37, v0
	s_mul_i32 s36, s36, s37
	s_mul_hi_u32 s36, s37, s36
	s_add_i32 s37, s37, s36
	s_mul_hi_u32 s36, s5, s37
	s_mul_i32 s37, s36, s30
	s_sub_i32 s5, s5, s37
	s_add_i32 s44, s36, 1
	s_sub_i32 s37, s5, s30
	s_cmp_ge_u32 s5, s30
	s_cselect_b32 s36, s44, s36
	s_cselect_b32 s5, s37, s5
	s_add_i32 s37, s36, 1
	s_cmp_ge_u32 s5, s30
	s_cselect_b32 s5, s37, s36
	s_xor_b32 s5, s5, s35
	s_sub_i32 s30, s5, s35
	s_mul_i32 s5, s30, s34
	s_sub_i32 s4, s4, s5
	s_add_i32 s34, s31, s4
	s_mul_i32 s100, s34, 0xaab
	s_lshr_b32 s100, s100, 16
	s_mul_i32 s101, s100, 24
	s_sub_i32 s101, s34, s101
	s_lshl_b32 s101, s101, 3
	s_or_b32 s34, s101, s100
.LBB0_171:
	s_nop 0
	v_cndmask_b32_e64 v0, 0, 1, s[0:1]
	v_cmp_ne_u32_e64 s[4:5], 1, v0
	s_andn2_b64 vcc, exec, s[0:1]
	s_mov_b64 s[0:1], s[40:41]
	s_mov_b64 s[36:37], s[42:43]
	s_cbranch_vccnz .LBB0_173
	s_lshr_b32 s100, s34, 5
	s_lshr_b32 s101, s8, 5
	s_cmp_lg_u32 s100, s101
	s_cbranch_scc0 .Lax_nowait
	s_cmp_lt_u32 s100, 2
	s_cbranch_scc1 .Lax_nowait
	v_readfirstlane_b32 s101, v190
	s_nop 0
	s_cmp_lt_u32 s101, 64
	s_cbranch_scc0 .Lax_nowait
	s_and_b32 s101, s34, 7
	s_lshl_b32 s101, s101, 3
	s_add_i32 s100, s100, s101
	s_lshl_b32 s100, s100, 4
	s_add_u32 s100, s100, s92
	s_addc_u32 s101, s93, 0
	s_add_u32 s100, s100, 0x3800
	s_addc_u32 s101, s101, 0
	s_waitcnt vmcnt(16)
	v_readfirstlane_b32 vcc_lo, v248
	s_nop 0
	s_cmp_ge_u32 vcc_lo, 64
	s_cbranch_scc1 .Lax_nowait
	v_mov_b32_e32 v201, 0
	s_movk_i32 vcc_hi, 0x4e20
.Lax_poll:
	global_load_dword v202, v201, s[100:101] sc1
	s_waitcnt vmcnt(0)
	v_readfirstlane_b32 vcc_lo, v202
	s_nop 0
	s_cmp_ge_u32 vcc_lo, 64
	s_cbranch_scc1 .Lax_nowait
	s_sleep 8
	s_sub_u32 vcc_hi, vcc_hi, 1
	s_cmp_lg_u32 vcc_hi, 0
	s_cbranch_scc1 .Lax_poll
.Lax_nowait:
	s_ashr_i32 s35, s34, 31
	s_lshl_b64 s[0:1], s[34:35], 19
	s_add_u32 s35, s25, s0
	s_addc_u32 s36, s29, s1
	s_ashr_i32 s31, s30, 31
	s_lshl_b64 s[0:1], s[30:31], 19
	s_add_u32 s31, s64, s0
	s_addc_u32 s37, s65, s1
	s_cmp_gt_i32 s30, 18
	s_cselect_b32 s1, s37, s36
	s_cselect_b32 s0, s31, s35
	s_cselect_b32 s37, s36, s37
	s_cselect_b32 s36, s35, s31

; #define PG8_STAGE(bufoff, gbase, voff) do { _Pragma("unroll") for (int _i = 0; _i < 2; ++_i) \
;         __builtin_amdgcn_global_load_lds((const unsigned*)((const char*)(gbase) + (voff)[_i]), (LAS unsigned*)(lds + (bufoff) + ldsw + _i * 8192), 16, 0, 0); } while (0)
; #define PG8_LDA(dst, b, h) do { _Pragma("unroll") for (int m = 0; m < 4; ++m) _Pragma("unroll") for (int k = 0; k < 2; ++k) dst[m][k] = *(const LAS bf16x8*)(lds + PG8_SA(b, h) + aoff + m * 2048 + k * 1024); } while (0)
; #define PG8_LDB(dst, b, h) do { _Pragma("unroll") for (int n = 0; n < 2; ++n) _Pragma("unroll") for (int k = 0; k < 2; ++k) dst[n][k] = *(const LAS bf16x8*)(lds + PG8_SB(b, h) + boff + n * 2048 + k * 1024); } while (0)
; #define PG8_MMA(ai, bj, At, Bt) do { __builtin_amdgcn_s_setprio(1); _Pragma("unroll") for (int m = 0; m < 4; ++m) _Pragma("unroll") for (int n = 0; n < 2; ++n) _Pragma("unroll") for (int k = 0; k < 2; ++k) \
;         acc[ai][bj][m][n] = __builtin_amdgcn_mfma_f32_16x16x32_bf16(Bt[n][k], At[m][k], acc[ai][bj][m][n], 0, 0, 0); __builtin_amdgcn_s_setprio(0); } while (0)
; #define PG8_WAIT_V(n) asm volatile("s_waitcnt vmcnt(" #n ")" ::: "memory")
; #define PG8_WAIT_L(n) asm volatile("s_waitcnt lgkmcnt(" #n ")" ::: "memory")
; #define PG8_BAR __builtin_amdgcn_s_barrier()
; #define PG8_SCHED __builtin_amdgcn_sched_barrier(0)
; template <class Epi, class Sched>
; __device__ __forceinline__ void gemm_phase(LAS unsigned char* lds, const Sched& S, const Epi& E, bool natural = false) {
;     ...
;             PG8_LDB(B0, 0, 0); PG8_LDB(B1, 0, 1); PG8_SCHED; PG8_LDA(At, 0, 0); PG8_STAGE(PG8_SA(1, 1), a1 + hstep, voffA);
;             PG8_WAIT_V(8); PG8_WAIT_L(0); PG8_BAR; PG8_MMA(0, 0, At, B0); PG8_MMA(0, 1, At, B1); PG8_BAR; PG8_SCHED;
;             PG8_LDA(At, 0, 1); PG8_STAGE(PG8_SB(0, 0), b2, voffB0); PG8_STAGE(PG8_SB(0, 1), b2, voffB1); PG8_STAGE(PG8_SA(0, 0), a2, voffA);
;             PG8_WAIT_V(8); PG8_WAIT_L(0); PG8_BAR; PG8_MMA(1, 0, At, B0); PG8_MMA(1, 1, At, B1); PG8_BAR; PG8_SCHED;
.LBB0_174:
	ds_read_b128 v[128:131], v196
	ds_read_b128 v[132:135], v196 offset:1024
	ds_read_b128 v[136:139], v196 offset:2048
	ds_read_b128 v[140:143], v196 offset:3072
	ds_read_b128 v[144:147], v197
	ds_read_b128 v[148:151], v197 offset:1024
	ds_read_b128 v[186:189], v197 offset:2048
	ds_read_b128 v[202:205], v197 offset:3072
	s_add_u32 s42, s40, 0xfffc0080
	s_addc_u32 s43, s41, -1
	s_cmp_eq_u32 s71, 12
	s_cselect_b32 s45, s1, s43
	s_cselect_b32 s44, s0, s42
	s_cselect_b32 s43, s37, s35
	s_cselect_b32 s42, s36, s31
	v_lshl_add_u64 v[238:239], s[40:41], 0, v[178:179]
	s_add_i32 m0, s39, 0xc000
	ds_read_b128 v[206:209], v198
	ds_read_b128 v[210:213], v198 offset:1024
	ds_read_b128 v[214:217], v198 offset:2048
	ds_read_b128 v[218:221], v198 offset:3072
	ds_read_b128 v[222:225], v198 offset:4096
	ds_read_b128 v[226:229], v198 offset:5120
	ds_read_b128 v[230:233], v198 offset:6144
	ds_read_b128 v[234:237], v198 offset:7168
	global_load_lds_dwordx4 v[238:239], off
	v_lshl_add_u64 v[238:239], s[40:41], 0, v[180:181]
	s_add_i32 m0, s39, 0xe000
	s_nop 0
	global_load_lds_dwordx4 v[238:239], off
	s_waitcnt vmcnt(8)
	s_waitcnt lgkmcnt(0)
	s_barrier
	s_setprio 1
	s_waitcnt lgkmcnt(0)
	v_mfma_f32_16x16x32_bf16 v[124:127], v[128:131], v[206:209], v[124:127]
	v_mfma_f32_16x16x32_bf16 v[120:123], v[136:139], v[206:209], v[120:123]
	v_mfma_f32_16x16x32_bf16 v[108:111], v[128:131], v[214:217], v[108:111]
	v_mfma_f32_16x16x32_bf16 v[104:107], v[136:139], v[214:217], v[104:107]
	v_mfma_f32_16x16x32_bf16 v[92:95], v[128:131], v[222:225], v[92:95]
	v_mfma_f32_16x16x32_bf16 v[88:91], v[136:139], v[222:225], v[88:91]
	v_mfma_f32_16x16x32_bf16 v[76:79], v[128:131], v[230:233], v[76:79]
	v_mfma_f32_16x16x32_bf16 v[72:75], v[136:139], v[230:233], v[72:75]
	v_mfma_f32_16x16x32_bf16 v[124:127], v[132:135], v[210:213], v[124:127]
	v_mfma_f32_16x16x32_bf16 v[120:123], v[140:143], v[210:213], v[120:123]
	v_mfma_f32_16x16x32_bf16 v[108:111], v[132:135], v[218:221], v[108:111]
	v_mfma_f32_16x16x32_bf16 v[104:107], v[140:143], v[218:221], v[104:107]
	v_mfma_f32_16x16x32_bf16 v[92:95], v[132:135], v[226:229], v[92:95]
	v_mfma_f32_16x16x32_bf16 v[88:91], v[140:143], v[226:229], v[88:91]
	v_mfma_f32_16x16x32_bf16 v[76:79], v[132:135], v[234:237], v[76:79]
	v_mfma_f32_16x16x32_bf16 v[72:75], v[140:143], v[234:237], v[72:75]
	s_setprio 0
	s_setprio 1
	v_mfma_f32_16x16x32_bf16 v[116:119], v[144:147], v[206:209], v[116:119]
	v_mfma_f32_16x16x32_bf16 v[112:115], v[186:189], v[206:209], v[112:115]
	v_mfma_f32_16x16x32_bf16 v[100:103], v[144:147], v[214:217], v[100:103]
	v_mfma_f32_16x16x32_bf16 v[96:99], v[186:189], v[214:217], v[96:99]
	v_mfma_f32_16x16x32_bf16 v[84:87], v[144:147], v[222:225], v[84:87]
	v_mfma_f32_16x16x32_bf16 v[80:83], v[186:189], v[222:225], v[80:83]
	v_mfma_f32_16x16x32_bf16 v[68:71], v[144:147], v[230:233], v[68:71]
	v_mfma_f32_16x16x32_bf16 v[64:67], v[186:189], v[230:233], v[64:67]
	v_mfma_f32_16x16x32_bf16 v[116:119], v[148:151], v[210:213], v[116:119]
	v_mfma_f32_16x16x32_bf16 v[112:115], v[202:205], v[210:213], v[112:115]
	v_mfma_f32_16x16x32_bf16 v[100:103], v[148:151], v[218:221], v[100:103]
	v_mfma_f32_16x16x32_bf16 v[96:99], v[202:205], v[218:221], v[96:99]
	v_mfma_f32_16x16x32_bf16 v[84:87], v[148:151], v[226:229], v[84:87]
	v_mfma_f32_16x16x32_bf16 v[80:83], v[202:205], v[226:229], v[80:83]
	v_mfma_f32_16x16x32_bf16 v[68:71], v[148:151], v[234:237], v[68:71]
	v_mfma_f32_16x16x32_bf16 v[64:67], v[202:205], v[234:237], v[64:67]
	s_setprio 0
	s_barrier
	s_add_i32 s72, s59, s33
	v_lshl_add_u64 v[238:239], s[42:43], 0, v[156:157]
	s_mov_b32 m0, s72
	ds_read_b128 v[206:209], v198 offset:16384
	ds_read_b128 v[210:213], v198 offset:17408
	ds_read_b128 v[214:217], v198 offset:18432
	ds_read_b128 v[218:221], v198 offset:19456
	ds_read_b128 v[222:225], v198 offset:20480
	ds_read_b128 v[226:229], v198 offset:21504
	ds_read_b128 v[230:233], v198 offset:22528
	ds_read_b128 v[234:237], v198 offset:23552
	global_load_lds_dwordx4 v[238:239], off
	v_lshl_add_u64 v[240:241], s[42:43], 0, v[162:163]
	s_add_i32 m0, s72, 0x2000
	s_add_i32 s72, s60, s33
	global_load_lds_dwordx4 v[240:241], off
	v_lshl_add_u64 v[242:243], s[42:43], 0, v[158:159]
	s_mov_b32 m0, s72
	v_lshl_add_u64 v[244:245], s[44:45], 0, v[160:161]
	global_load_lds_dwordx4 v[242:243], off
	v_lshl_add_u64 v[242:243], s[42:43], 0, v[164:165]
	s_add_i32 m0, s72, 0x2000
	s_nop 0
	global_load_lds_dwordx4 v[242:243], off
	v_lshl_add_u64 v[242:243], s[44:45], 0, v[154:155]
	s_mov_b32 m0, s39
	s_nop 0
	global_load_lds_dwordx4 v[242:243], off
	s_mov_b32 m0, s46
	s_nop 0
	global_load_lds_dwordx4 v[244:245], off
	s_waitcnt vmcnt(8)
	s_waitcnt lgkmcnt(0)
	s_barrier
; #define PG8_STAGE(bufoff, gbase, voff) do { _Pragma("unroll") for (int _i = 0; _i < 2; ++_i) \
;         __builtin_amdgcn_global_load_lds((const unsigned*)((const char*)(gbase) + (voff)[_i]), (LAS unsigned*)(lds + (bufoff) + ldsw + _i * 8192), 16, 0, 0); } while (0)
; #define PG8_LDA(dst, b, h) do { _Pragma("unroll") for (int m = 0; m < 4; ++m) _Pragma("unroll") for (int k = 0; k < 2; ++k) dst[m][k] = *(const LAS bf16x8*)(lds + PG8_SA(b, h) + aoff + m * 2048 + k * 1024); } while (0)
; #define PG8_LDB(dst, b, h) do { _Pragma("unroll") for (int n = 0; n < 2; ++n) _Pragma("unroll") for (int k = 0; k < 2; ++k) dst[n][k] = *(const LAS bf16x8*)(lds + PG8_SB(b, h) + boff + n * 2048 + k * 1024); } while (0)
; #define PG8_MMA(ai, bj, At, Bt) do { __builtin_amdgcn_s_setprio(1); _Pragma("unroll") for (int m = 0; m < 4; ++m) _Pragma("unroll") for (int n = 0; n < 2; ++n) _Pragma("unroll") for (int k = 0; k < 2; ++k) \
;         acc[ai][bj][m][n] = __builtin_amdgcn_mfma_f32_16x16x32_bf16(Bt[n][k], At[m][k], acc[ai][bj][m][n], 0, 0, 0); __builtin_amdgcn_s_setprio(0); } while (0)
; #define PG8_WAIT_V(n) asm volatile("s_waitcnt vmcnt(" #n ")" ::: "memory")
; #define PG8_WAIT_L(n) asm volatile("s_waitcnt lgkmcnt(" #n ")" ::: "memory")
; #define PG8_BAR __builtin_amdgcn_s_barrier()
; #define PG8_SCHED __builtin_amdgcn_sched_barrier(0)
; template <class Epi, class Sched>
; __device__ __forceinline__ void gemm_phase(LAS unsigned char* lds, const Sched& S, const Epi& E, bool natural = false) {
;     ...
;             PG8_WAIT_V(8); PG8_WAIT_L(0); PG8_BAR; PG8_MMA(1, 0, At, B0); PG8_MMA(1, 1, At, B1); PG8_BAR; PG8_SCHED;
;             PG8_LDB(B0, 1, 0); PG8_LDB(B1, 1, 1); PG8_SCHED; PG8_LDA(At, 1, 0); PG8_STAGE(PG8_SA(0, 1), a2 + hstep, voffA);
;             PG8_WAIT_V(8); PG8_WAIT_L(0); PG8_BAR; PG8_MMA(0, 0, At, B0); PG8_MMA(0, 1, At, B1); PG8_BAR; PG8_SCHED;
	s_setprio 1
	s_waitcnt lgkmcnt(0)
	v_mfma_f32_16x16x32_bf16 v[60:63], v[128:131], v[206:209], v[60:63]
	v_mfma_f32_16x16x32_bf16 v[56:59], v[136:139], v[206:209], v[56:59]
	v_mfma_f32_16x16x32_bf16 v[44:47], v[128:131], v[214:217], v[44:47]
	v_mfma_f32_16x16x32_bf16 v[40:43], v[136:139], v[214:217], v[40:43]
	v_mfma_f32_16x16x32_bf16 v[28:31], v[128:131], v[222:225], v[28:31]
	v_mfma_f32_16x16x32_bf16 v[24:27], v[136:139], v[222:225], v[24:27]
	v_mfma_f32_16x16x32_bf16 v[12:15], v[128:131], v[230:233], v[12:15]
	v_mfma_f32_16x16x32_bf16 v[8:11], v[136:139], v[230:233], v[8:11]
	v_mfma_f32_16x16x32_bf16 v[60:63], v[132:135], v[210:213], v[60:63]
	v_mfma_f32_16x16x32_bf16 v[56:59], v[140:143], v[210:213], v[56:59]
	v_mfma_f32_16x16x32_bf16 v[44:47], v[132:135], v[218:221], v[44:47]
	v_mfma_f32_16x16x32_bf16 v[40:43], v[140:143], v[218:221], v[40:43]
	v_mfma_f32_16x16x32_bf16 v[28:31], v[132:135], v[226:229], v[28:31]
	v_mfma_f32_16x16x32_bf16 v[24:27], v[140:143], v[226:229], v[24:27]
	v_mfma_f32_16x16x32_bf16 v[12:15], v[132:135], v[234:237], v[12:15]
	v_mfma_f32_16x16x32_bf16 v[8:11], v[140:143], v[234:237], v[8:11]
	s_setprio 0
	s_setprio 1
	v_mfma_f32_16x16x32_bf16 v[52:55], v[144:147], v[206:209], v[52:55]
	v_mfma_f32_16x16x32_bf16 v[48:51], v[186:189], v[206:209], v[48:51]
	v_mfma_f32_16x16x32_bf16 v[36:39], v[144:147], v[214:217], v[36:39]
	v_mfma_f32_16x16x32_bf16 v[32:35], v[186:189], v[214:217], v[32:35]
	v_mfma_f32_16x16x32_bf16 v[20:23], v[144:147], v[222:225], v[20:23]
	v_mfma_f32_16x16x32_bf16 v[16:19], v[186:189], v[222:225], v[16:19]
	v_mfma_f32_16x16x32_bf16 v[4:7], v[144:147], v[230:233], v[4:7]
	v_mfma_f32_16x16x32_bf16 v[0:3], v[186:189], v[230:233], v[0:3]
	v_mfma_f32_16x16x32_bf16 v[52:55], v[148:151], v[210:213], v[52:55]
	v_mfma_f32_16x16x32_bf16 v[48:51], v[202:205], v[210:213], v[48:51]
	v_mfma_f32_16x16x32_bf16 v[36:39], v[148:151], v[218:221], v[36:39]
	v_mfma_f32_16x16x32_bf16 v[32:35], v[202:205], v[218:221], v[32:35]
	v_mfma_f32_16x16x32_bf16 v[20:23], v[148:151], v[226:229], v[20:23]
	v_mfma_f32_16x16x32_bf16 v[16:19], v[202:205], v[226:229], v[16:19]
	v_mfma_f32_16x16x32_bf16 v[4:7], v[148:151], v[234:237], v[4:7]
	v_mfma_f32_16x16x32_bf16 v[0:3], v[202:205], v[234:237], v[0:3]
	s_setprio 0
	s_barrier
	s_add_i32 s72, 0, 0x18000
	s_add_i32 s73, 0, 0x1c000
	v_add_u32_e32 v140, s72, v192
	v_add_u32_e32 v166, s73, v192
	ds_read_b128 v[128:131], v140
	ds_read_b128 v[132:135], v140 offset:1024
	ds_read_b128 v[136:139], v140 offset:2048
	ds_read_b128 v[140:143], v140 offset:3072
	ds_read_b128 v[144:147], v166
	ds_read_b128 v[148:151], v166 offset:1024
	ds_read_b128 v[186:189], v166 offset:2048
	ds_read_b128 v[202:205], v166 offset:3072
	s_add_u32 s44, s44, 0x40000
	s_addc_u32 s45, s45, 0
	s_mov_b32 m0, s47
	v_lshl_add_u64 v[246:247], s[44:45], 0, v[154:155]
	ds_read_b128 v[206:209], v198 offset:32768
	ds_read_b128 v[210:213], v198 offset:33792
	ds_read_b128 v[214:217], v198 offset:34816
	ds_read_b128 v[218:221], v198 offset:35840
	ds_read_b128 v[222:225], v198 offset:36864
	ds_read_b128 v[226:229], v198 offset:37888
	ds_read_b128 v[230:233], v198 offset:38912
	ds_read_b128 v[234:237], v198 offset:39936
	global_load_lds_dwordx4 v[246:247], off
	v_lshl_add_u64 v[246:247], s[44:45], 0, v[160:161]
	s_mov_b32 m0, s49
	s_nop 0
	global_load_lds_dwordx4 v[246:247], off
	s_waitcnt vmcnt(8)
	s_waitcnt lgkmcnt(0)
	s_barrier
	s_setprio 1
	s_waitcnt lgkmcnt(0)
	v_mfma_f32_16x16x32_bf16 v[124:127], v[128:131], v[206:209], v[124:127]
	v_mfma_f32_16x16x32_bf16 v[120:123], v[136:139], v[206:209], v[120:123]
	v_mfma_f32_16x16x32_bf16 v[108:111], v[128:131], v[214:217], v[108:111]
	v_mfma_f32_16x16x32_bf16 v[104:107], v[136:139], v[214:217], v[104:107]
	v_mfma_f32_16x16x32_bf16 v[92:95], v[128:131], v[222:225], v[92:95]
	v_mfma_f32_16x16x32_bf16 v[88:91], v[136:139], v[222:225], v[88:91]
	v_mfma_f32_16x16x32_bf16 v[76:79], v[128:131], v[230:233], v[76:79]
	v_mfma_f32_16x16x32_bf16 v[72:75], v[136:139], v[230:233], v[72:75]
	v_mfma_f32_16x16x32_bf16 v[124:127], v[132:135], v[210:213], v[124:127]
	v_mfma_f32_16x16x32_bf16 v[120:123], v[140:143], v[210:213], v[120:123]
	v_mfma_f32_16x16x32_bf16 v[108:111], v[132:135], v[218:221], v[108:111]
	v_mfma_f32_16x16x32_bf16 v[104:107], v[140:143], v[218:221], v[104:107]
	v_mfma_f32_16x16x32_bf16 v[92:95], v[132:135], v[226:229], v[92:95]
	v_mfma_f32_16x16x32_bf16 v[88:91], v[140:143], v[226:229], v[88:91]
	v_mfma_f32_16x16x32_bf16 v[76:79], v[132:135], v[234:237], v[76:79]
	v_mfma_f32_16x16x32_bf16 v[72:75], v[140:143], v[234:237], v[72:75]
	s_setprio 0
	s_setprio 1
	v_mfma_f32_16x16x32_bf16 v[116:119], v[144:147], v[206:209], v[116:119]
	v_mfma_f32_16x16x32_bf16 v[112:115], v[186:189], v[206:209], v[112:115]
	v_mfma_f32_16x16x32_bf16 v[100:103], v[144:147], v[214:217], v[100:103]
	v_mfma_f32_16x16x32_bf16 v[96:99], v[186:189], v[214:217], v[96:99]
	v_mfma_f32_16x16x32_bf16 v[84:87], v[144:147], v[222:225], v[84:87]
	v_mfma_f32_16x16x32_bf16 v[80:83], v[186:189], v[222:225], v[80:83]
	v_mfma_f32_16x16x32_bf16 v[68:71], v[144:147], v[230:233], v[68:71]
	v_mfma_f32_16x16x32_bf16 v[64:67], v[186:189], v[230:233], v[64:67]
	v_mfma_f32_16x16x32_bf16 v[116:119], v[148:151], v[210:213], v[116:119]
	v_mfma_f32_16x16x32_bf16 v[112:115], v[202:205], v[210:213], v[112:115]
	v_mfma_f32_16x16x32_bf16 v[100:103], v[148:151], v[218:221], v[100:103]
	v_mfma_f32_16x16x32_bf16 v[96:99], v[202:205], v[218:221], v[96:99]
	v_mfma_f32_16x16x32_bf16 v[84:87], v[148:151], v[226:229], v[84:87]
	v_mfma_f32_16x16x32_bf16 v[80:83], v[202:205], v[226:229], v[80:83]
	v_mfma_f32_16x16x32_bf16 v[68:71], v[148:151], v[234:237], v[68:71]
	v_mfma_f32_16x16x32_bf16 v[64:67], v[202:205], v[234:237], v[64:67]
	s_setprio 0
	s_barrier
; #define PG8_STAGE(bufoff, gbase, voff) do { _Pragma("unroll") for (int _i = 0; _i < 2; ++_i) \
;         __builtin_amdgcn_global_load_lds((const unsigned*)((const char*)(gbase) + (voff)[_i]), (LAS unsigned*)(lds + (bufoff) + ldsw + _i * 8192), 16, 0, 0); } while (0)
; #define PG8_LDA(dst, b, h) do { _Pragma("unroll") for (int m = 0; m < 4; ++m) _Pragma("unroll") for (int k = 0; k < 2; ++k) dst[m][k] = *(const LAS bf16x8*)(lds + PG8_SA(b, h) + aoff + m * 2048 + k * 1024); } while (0)
; #define PG8_MMA(ai, bj, At, Bt) do { __builtin_amdgcn_s_setprio(1); _Pragma("unroll") for (int m = 0; m < 4; ++m) _Pragma("unroll") for (int n = 0; n < 2; ++n) _Pragma("unroll") for (int k = 0; k < 2; ++k) \
;         acc[ai][bj][m][n] = __builtin_amdgcn_mfma_f32_16x16x32_bf16(Bt[n][k], At[m][k], acc[ai][bj][m][n], 0, 0, 0); __builtin_amdgcn_s_setprio(0); } while (0)
; #define PG8_WAIT_V(n) asm volatile("s_waitcnt vmcnt(" #n ")" ::: "memory")
; #define PG8_WAIT_L(n) asm volatile("s_waitcnt lgkmcnt(" #n ")" ::: "memory")
; #define PG8_BAR __builtin_amdgcn_s_barrier()
; #define PG8_SCHED __builtin_amdgcn_sched_barrier(0)
; template <class Epi, class Sched>
; __device__ __forceinline__ void gemm_phase(LAS unsigned char* lds, const Sched& S, const Epi& E, bool natural = false) {
;     ...
;             PG8_LDA(At, 1, 1); PG8_STAGE(PG8_SB(1, 0), b3, voffB0); PG8_STAGE(PG8_SB(1, 1), b3, voffB1); PG8_STAGE(PG8_SA(1, 0), a3, voffA);
;             PG8_WAIT_V(8); PG8_WAIT_L(0); PG8_BAR; PG8_MMA(1, 0, At, B0); PG8_MMA(1, 1, At, B1); PG8_BAR; PG8_SCHED;
;         }
;         if (wr == 0) PG8_BAR;
;         E(acc, cur, wr, wc, fr, fq);
	s_add_u32 s42, s42, 0x80
	s_addc_u32 s43, s43, 0
	s_add_i32 s44, s72, s33
	v_lshl_add_u64 v[238:239], v[238:239], 0, s[12:13]
	s_mov_b32 m0, s44
	ds_read_b128 v[206:209], v198 offset:49152
	ds_read_b128 v[210:213], v198 offset:50176
	ds_read_b128 v[214:217], v198 offset:51200
	ds_read_b128 v[218:221], v198 offset:52224
	ds_read_b128 v[222:225], v198 offset:53248
	ds_read_b128 v[226:229], v198 offset:54272
	ds_read_b128 v[230:233], v198 offset:55296
	ds_read_b128 v[234:237], v198 offset:56320
	global_load_lds_dwordx4 v[238:239], off
	v_lshl_add_u64 v[238:239], v[240:241], 0, s[12:13]
	s_add_i32 m0, s44, 0x2000
	s_add_i32 s44, s73, s33
	global_load_lds_dwordx4 v[238:239], off
	v_lshl_add_u64 v[238:239], s[42:43], 0, v[158:159]
	s_mov_b32 m0, s44
	s_nop 0
	global_load_lds_dwordx4 v[238:239], off
	v_lshl_add_u64 v[238:239], s[42:43], 0, v[164:165]
	s_add_i32 m0, s44, 0x2000
	s_nop 0
	global_load_lds_dwordx4 v[238:239], off
	v_lshl_add_u64 v[238:239], v[242:243], 0, s[12:13]
	s_mov_b32 m0, s51
	s_nop 0
	global_load_lds_dwordx4 v[238:239], off
	v_lshl_add_u64 v[238:239], v[244:245], 0, s[12:13]
	s_mov_b32 m0, s52
	s_nop 0
	global_load_lds_dwordx4 v[238:239], off
	s_waitcnt vmcnt(8)
	s_waitcnt lgkmcnt(0)
	s_barrier
	s_setprio 1
	s_waitcnt lgkmcnt(0)
	v_mfma_f32_16x16x32_bf16 v[60:63], v[128:131], v[206:209], v[60:63]
	v_mfma_f32_16x16x32_bf16 v[56:59], v[136:139], v[206:209], v[56:59]
	v_mfma_f32_16x16x32_bf16 v[44:47], v[128:131], v[214:217], v[44:47]
	v_mfma_f32_16x16x32_bf16 v[40:43], v[136:139], v[214:217], v[40:43]
	v_mfma_f32_16x16x32_bf16 v[28:31], v[128:131], v[222:225], v[28:31]
	v_mfma_f32_16x16x32_bf16 v[24:27], v[136:139], v[222:225], v[24:27]
	v_mfma_f32_16x16x32_bf16 v[12:15], v[128:131], v[230:233], v[12:15]
	v_mfma_f32_16x16x32_bf16 v[8:11], v[136:139], v[230:233], v[8:11]
	v_mfma_f32_16x16x32_bf16 v[60:63], v[132:135], v[210:213], v[60:63]
	v_mfma_f32_16x16x32_bf16 v[56:59], v[140:143], v[210:213], v[56:59]
	v_mfma_f32_16x16x32_bf16 v[44:47], v[132:135], v[218:221], v[44:47]
	v_mfma_f32_16x16x32_bf16 v[40:43], v[140:143], v[218:221], v[40:43]
	v_mfma_f32_16x16x32_bf16 v[28:31], v[132:135], v[226:229], v[28:31]
	v_mfma_f32_16x16x32_bf16 v[24:27], v[140:143], v[226:229], v[24:27]
	v_mfma_f32_16x16x32_bf16 v[12:15], v[132:135], v[234:237], v[12:15]
	v_mfma_f32_16x16x32_bf16 v[8:11], v[140:143], v[234:237], v[8:11]
	s_setprio 0
	s_setprio 1
	v_mfma_f32_16x16x32_bf16 v[52:55], v[144:147], v[206:209], v[52:55]
	v_mfma_f32_16x16x32_bf16 v[48:51], v[186:189], v[206:209], v[48:51]
	v_mfma_f32_16x16x32_bf16 v[36:39], v[144:147], v[214:217], v[36:39]
	v_mfma_f32_16x16x32_bf16 v[32:35], v[186:189], v[214:217], v[32:35]
	v_mfma_f32_16x16x32_bf16 v[20:23], v[144:147], v[222:225], v[20:23]
	v_mfma_f32_16x16x32_bf16 v[16:19], v[186:189], v[222:225], v[16:19]
	v_mfma_f32_16x16x32_bf16 v[4:7], v[144:147], v[230:233], v[4:7]
	v_mfma_f32_16x16x32_bf16 v[0:3], v[186:189], v[230:233], v[0:3]
	v_mfma_f32_16x16x32_bf16 v[52:55], v[148:151], v[210:213], v[52:55]
	v_mfma_f32_16x16x32_bf16 v[48:51], v[202:205], v[210:213], v[48:51]
	v_mfma_f32_16x16x32_bf16 v[36:39], v[148:151], v[218:221], v[36:39]
	v_mfma_f32_16x16x32_bf16 v[32:35], v[202:205], v[218:221], v[32:35]
	v_mfma_f32_16x16x32_bf16 v[20:23], v[148:151], v[226:229], v[20:23]
	v_mfma_f32_16x16x32_bf16 v[16:19], v[202:205], v[226:229], v[16:19]
	v_mfma_f32_16x16x32_bf16 v[4:7], v[148:151], v[234:237], v[4:7]
	v_mfma_f32_16x16x32_bf16 v[0:3], v[202:205], v[234:237], v[0:3]
	s_setprio 0
	s_barrier
	s_add_i32 s71, s71, 2
	s_add_u32 s40, s40, 0x100
	s_addc_u32 s41, s41, 0
	s_add_u32 s31, s31, 0x100
	s_addc_u32 s35, s35, 0
	s_cmp_gt_u32 s71, 13
	s_cbranch_scc0 .LBB0_174
	s_and_b64 vcc, exec, s[14:15]
	s_cbranch_vccz .LBB0_179
	s_barrier
	s_branch .LBB0_179

;     __device__ __forceinline__ void qk(const AccT& acc, int row0, int wr, int fr, int fq, bf16_t* dst, int ld, int colh, const float* w, float scale, bool rope) const {
;         f32x4 wv[2][2];
;         int fq8 = 8 * fq; asm volatile("" : "+v"(fq8));
; #pragma unroll
;         for (int bj = 0; bj < 2; ++bj)
; #pragma unroll
;             for (int n = 0; n < 2; ++n) wv[bj][n] = *(const f32x4*)(w + 32 * bj + fq8 + 4 * n) * scale;
;         f32x4 irev[2];
; #pragma unroll
;         for (int n = 0; n < 2; ++n) irev[n] = rope ? *(const f32x4*)(ROPE_IREV + fq8 + 4 * n) : (f32x4){0.f, 0.f, 0.f, 0.f};
; #pragma unroll
;         for (int ai = 0; ai < 2; ++ai)
; #pragma unroll
;             for (int m = 0; m < 4; ++m) {
;                 const int r = row0 + 128 * ai + 64 * wr + 16 * m + fr;
;                 f32x4 v[2][2]; float ss = 0.f;
; #pragma unroll
;                 for (int bj = 0; bj < 2; ++bj)
; #pragma unroll
;                     for (int n = 0; n < 2; ++n) { v[bj][n] = acc[ai][bj][m][n]; const f32x4 x = v[bj][n]; ss += (x[0] * x[0] + x[1] * x[1]) + (x[2] * x[2] + x[3] * x[3]); }
;                 ss += __shfl_xor(ss, 16); ss += __shfl_xor(ss, 32);
;                 const float inv = __builtin_amdgcn_rsqf(ss * (1.0f / 64.0f) + NORM_EPS);
; #pragma unroll
;                 for (int bj = 0; bj < 2; ++bj)
; #pragma unroll
;                     for (int n = 0; n < 2; ++n) v[bj][n] = v[bj][n] * inv * wv[bj][n];
.LBB0_178:
	s_nop 0
	v_mov_b32_e32 v128, v152
	v_pk_mul_f32 v[130:131], v[126:127], v[126:127]
	v_ashrrev_i32_e32 v129, 31, v128
	v_lshl_add_u64 v[128:129], v[128:129], 2, s[84:85]
	global_load_dwordx4 v[134:137], v[128:129], off
	global_load_dwordx4 v[138:141], v[128:129], off offset:16
	global_load_dwordx4 v[142:145], v[128:129], off offset:128
	global_load_dwordx4 v[146:149], v[128:129], off offset:144
	v_pk_mul_f32 v[132:133], v[124:125], v[124:125]
	v_pk_mul_f32 v[150:151], v[122:123], v[122:123]
	v_pk_mul_f32 v[186:187], v[120:121], v[120:121]
	v_pk_mov_b32 v[202:203], v[132:133], v[130:131] op_sel:[1,0]
	v_mov_b32_e32 v133, v131
	v_pk_mov_b32 v[130:131], v[186:187], v[150:151] op_sel:[1,0]
	v_mov_b32_e32 v187, v151
	v_and_b32_e32 v189, 64, v200
	v_mul_f32_e32 v166, v117, v117
	v_mul_f32_e32 v188, v119, v119
	v_pk_add_f32 v[202:203], v[202:203], v[132:133]
	v_pk_add_f32 v[130:131], v[130:131], v[186:187]
	v_mul_f32_e32 v204, v112, v112
	v_mul_f32_e32 v205, v113, v113
	v_mul_f32_e32 v206, v114, v114
	v_mul_f32_e32 v207, v115, v115
	v_add_u32_e32 v208, 64, v189
	v_pk_fma_f32 v[150:151], v[116:117], v[116:117], v[166:167] op_sel_hi:[1,1,0]
	v_pk_fma_f32 v[188:189], v[118:119], v[118:119], v[188:189] op_sel_hi:[1,1,0]
	v_pk_add_f32 v[186:187], v[202:203], v[202:203] op_sel:[0,1] op_sel_hi:[1,0]
	v_pk_add_f32 v[130:131], v[130:131], v[130:131] op_sel:[0,1] op_sel_hi:[1,0]
	v_xor_b32_e32 v129, 16, v200
	v_mov_b32_e32 v151, v206
	v_mov_b32_e32 v189, v207
	v_mov_b32_e32 v187, v204
	v_mov_b32_e32 v131, v205
	v_cmp_lt_i32_e32 vcc, v129, v208
	v_pk_add_f32 v[150:151], v[150:151], v[188:189]
	v_pk_add_f32 v[130:131], v[186:187], v[130:131]
	v_cndmask_b32_e32 v129, v200, v129, vcc
	v_pk_add_f32 v[130:131], v[130:131], v[150:151]
	v_lshlrev_b32_e32 v132, 2, v129
	v_add_f32_e32 v129, v130, v131
	ds_bpermute_b32 v130, v132, v129
	v_xor_b32_e32 v201, 32, v200
	v_cmp_lt_i32_e32 vcc, v201, v208
	v_pk_mul_f32 v[150:151], v[110:111], v[110:111]
	v_pk_mul_f32 v[186:187], v[108:109], v[108:109]
	v_cndmask_b32_e32 v131, v200, v201, vcc
	v_lshlrev_b32_e32 v133, 2, v131
	s_waitcnt lgkmcnt(0)
	v_add_f32_e32 v130, v129, v130
	ds_bpermute_b32 v131, v133, v130
	v_pk_mov_b32 v[188:189], v[186:187], v[150:151] op_sel:[1,0]
	v_mov_b32_e32 v187, v151
	v_add_u32_e32 v128, s31, v153
	v_ashrrev_i32_e32 v129, 31, v128
	s_waitcnt lgkmcnt(0)
	v_add_f32_e32 v130, v130, v131
	v_fmamk_f32 v130, v130, 0x3c800000, v199
	v_rsq_f32_e32 v150, v130
	v_lshlrev_b64 v[202:203], 10, v[128:129]
	v_mul_f32_e32 v129, v96, v96
	v_mul_f32_e32 v166, v97, v97
	v_pk_mul_f32 v[204:205], v[124:125], v[150:151] op_sel_hi:[1,0]
	v_pk_mul_f32 v[206:207], v[126:127], v[150:151] op_sel_hi:[1,0]
	v_pk_mul_f32 v[208:209], v[120:121], v[150:151] op_sel_hi:[1,0]
	v_pk_mul_f32 v[210:211], v[122:123], v[150:151] op_sel_hi:[1,0]
	v_pk_mul_f32 v[212:213], v[116:117], v[150:151] op_sel_hi:[1,0]
	v_pk_mul_f32 v[214:215], v[118:119], v[150:151] op_sel_hi:[1,0]
	v_pk_mul_f32 v[216:217], v[112:113], v[150:151] op_sel_hi:[1,0]
	v_pk_mul_f32 v[218:219], v[114:115], v[150:151] op_sel_hi:[1,0]
	v_pk_add_f32 v[150:151], v[188:189], v[186:187]
	v_pk_mul_f32 v[186:187], v[106:107], v[106:107]
	v_pk_mul_f32 v[188:189], v[104:105], v[104:105]
	v_pk_add_f32 v[150:151], v[150:151], v[150:151] op_sel:[0,1] op_sel_hi:[1,0]
	v_mul_f32_e32 v201, v99, v99
	v_mov_b32_e32 v151, v129
	s_lshl_b32 s8, s38, 8
	s_or_b32 s40, s8, s53
	s_ashr_i32 s41, s40, 31
	v_lshl_add_u64 v[130:131], s[40:41], 1, v[176:177]
	s_waitcnt vmcnt(0)
	v_pk_mul_f32 v[122:123], v[134:135], s[28:29] op_sel_hi:[1,0]
	s_nop 0
	v_pk_mul_f32 v[134:135], v[122:123], v[204:205]
	v_pk_mov_b32 v[204:205], v[188:189], v[186:187] op_sel:[1,0]
	v_mov_b32_e32 v189, v187
	v_pk_add_f32 v[186:187], v[204:205], v[188:189]
	v_mul_f32_e32 v188, v98, v98
	v_pk_add_f32 v[186:187], v[186:187], v[186:187] op_sel:[0,1] op_sel_hi:[1,0]
	v_pk_mul_f32 v[126:127], v[136:137], s[28:29] op_sel_hi:[1,0]
	v_mov_b32_e32 v187, v166
	v_mul_f32_e32 v166, v101, v101
	v_pk_add_f32 v[150:151], v[150:151], v[186:187]
	v_pk_fma_f32 v[186:187], v[100:101], v[100:101], v[166:167] op_sel_hi:[1,1,0]
	v_mul_f32_e32 v166, v103, v103
	v_mov_b32_e32 v187, v188
	v_pk_fma_f32 v[188:189], v[102:103], v[102:103], v[166:167] op_sel_hi:[1,1,0]
	v_pk_mul_f32 v[118:119], v[138:139], s[28:29] op_sel_hi:[1,0]
	v_mov_b32_e32 v189, v201
	v_pk_add_f32 v[186:187], v[186:187], v[188:189]
	v_pk_mul_f32 v[124:125], v[140:141], s[28:29] op_sel_hi:[1,0]
	v_pk_add_f32 v[150:151], v[150:151], v[186:187]
	v_pk_mul_f32 v[136:137], v[126:127], v[206:207]
	v_add_f32_e32 v129, v150, v151
	ds_bpermute_b32 v166, v132, v129
	v_pk_mul_f32 v[140:141], v[118:119], v[208:209]
	v_cvt_pk_bf16_f32 v134, v134, v135
	v_cvt_pk_bf16_f32 v135, v136, v137
	v_cvt_pk_bf16_f32 v136, v140, v141
	s_waitcnt lgkmcnt(0)
	v_add_f32_e32 v129, v129, v166
	ds_bpermute_b32 v140, v133, v129
	v_pk_mul_f32 v[138:139], v[124:125], v[210:211]
	v_pk_mul_f32 v[116:117], v[142:143], s[28:29] op_sel_hi:[1,0]
	v_cvt_pk_bf16_f32 v137, v138, v139
	v_pk_mul_f32 v[120:121], v[144:145], s[28:29] op_sel_hi:[1,0]
	s_waitcnt lgkmcnt(0)
; __device__ __forceinline__ unsigned cvt_pk_bf16(float lo, float hi) { const f32x2_t v = {lo, hi}; const bf16x2_t r = __builtin_convertvector(v, bf16x2_t); return __builtin_bit_cast(unsigned, r); }
;     __device__ __forceinline__ void qk(const AccT& acc, int row0, int wr, int fr, int fq, bf16_t* dst, int ld, int colh, const float* w, float scale, bool rope) const {
;     ...
;                 const int r = row0 + 128 * ai + 64 * wr + 16 * m + fr;
;                 f32x4 v[2][2]; float ss = 0.f;
; #pragma unroll
;                 for (int bj = 0; bj < 2; ++bj)
; #pragma unroll
;                     for (int n = 0; n < 2; ++n) { v[bj][n] = acc[ai][bj][m][n]; const f32x4 x = v[bj][n]; ss += (x[0] * x[0] + x[1] * x[1]) + (x[2] * x[2] + x[3] * x[3]); }
;                 ss += __shfl_xor(ss, 16); ss += __shfl_xor(ss, 32);
;                 const float inv = __builtin_amdgcn_rsqf(ss * (1.0f / 64.0f) + NORM_EPS);
; #pragma unroll
;                 for (int bj = 0; bj < 2; ++bj)
; #pragma unroll
;                     for (int n = 0; n < 2; ++n) v[bj][n] = v[bj][n] * inv * wv[bj][n];
;                 if (rope) {
;                     const float fp = (float)(r & (SEQ - 1));
; #pragma unroll
;                     for (int n = 0; n < 2; ++n) {
;                         f32x4 c, s;
; #pragma unroll
;                         for (int j = 0; j < 4; ++j) { const float fr_ = __builtin_amdgcn_fractf(fp * irev[n][j]); c[j] = __builtin_amdgcn_cosf(fr_); s[j] = __builtin_amdgcn_sinf(fr_); }
;                         const f32x4 x1 = v[0][n], x2 = v[1][n];
;                         v[0][n] = x1 * c - x2 * s; v[1][n] = x2 * c + x1 * s;
;                     }
;                 }
;                 bf16_t* rowp = dst + (size_t)r * ld + colh + 8 * fq;
; #pragma unroll
;                 for (int bj = 0; bj < 2; ++bj) { u32x4 o; o.x = cvt_pk_bf16(v[bj][0][0], v[bj][0][1]); o.y = cvt_pk_bf16(v[bj][0][2], v[bj][0][3]); o.z = cvt_pk_bf16(v[bj][1][0], v[bj][1][1]); o.w = cvt_pk_bf16(v[bj][1][2], v[bj][1][3]);
;                     *(u32x4*)(rowp + 32 * bj) = o; }
	v_add_f32_e32 v129, v129, v140
	v_fmamk_f32 v129, v129, 0x3c800000, v199
	v_rsq_f32_e32 v138, v129
	v_pk_mul_f32 v[112:113], v[146:147], s[28:29] op_sel_hi:[1,0]
	v_pk_mul_f32 v[114:115], v[148:149], s[28:29] op_sel_hi:[1,0]
	v_pk_mul_f32 v[142:143], v[120:121], v[214:215]
	v_pk_mul_f32 v[144:145], v[116:117], v[212:213]
	v_pk_mul_f32 v[146:147], v[114:115], v[218:219]
	v_pk_mul_f32 v[148:149], v[112:113], v[216:217]
	v_lshl_add_u64 v[150:151], v[130:131], 0, v[202:203]
	global_store_dwordx4 v[150:151], v[134:137], off
	v_pk_mul_f32 v[98:99], v[98:99], v[138:139] op_sel_hi:[1,0]
	v_pk_mul_f32 v[108:109], v[108:109], v[138:139] op_sel_hi:[1,0]
	v_cvt_pk_bf16_f32 v134, v144, v145
	v_cvt_pk_bf16_f32 v135, v142, v143
	v_cvt_pk_bf16_f32 v136, v148, v149
	v_cvt_pk_bf16_f32 v137, v146, v147
	global_store_dwordx4 v[150:151], v[134:137], off offset:64
	v_pk_mul_f32 v[110:111], v[110:111], v[138:139] op_sel_hi:[1,0]
	v_pk_mul_f32 v[104:105], v[104:105], v[138:139] op_sel_hi:[1,0]
	v_pk_mul_f32 v[106:107], v[106:107], v[138:139] op_sel_hi:[1,0]
	v_pk_mul_f32 v[100:101], v[100:101], v[138:139] op_sel_hi:[1,0]
	v_pk_mul_f32 v[102:103], v[102:103], v[138:139] op_sel_hi:[1,0]
	v_pk_mul_f32 v[96:97], v[96:97], v[138:139] op_sel_hi:[1,0]
	v_pk_mul_f32 v[134:135], v[114:115], v[98:99]
	v_pk_mul_f32 v[98:99], v[94:95], v[94:95]
	v_pk_mul_f32 v[138:139], v[92:93], v[92:93]
	v_mul_f32_e32 v129, v80, v80
	v_pk_mov_b32 v[140:141], v[138:139], v[98:99] op_sel:[1,0]
	v_mov_b32_e32 v139, v99
	v_pk_add_f32 v[98:99], v[140:141], v[138:139]
	v_pk_mul_f32 v[138:139], v[90:91], v[90:91]
	v_pk_mul_f32 v[140:141], v[88:89], v[88:89]
	v_pk_add_f32 v[98:99], v[98:99], v[98:99] op_sel:[0,1] op_sel_hi:[1,0]
	v_pk_mov_b32 v[142:143], v[140:141], v[138:139] op_sel:[1,0]
	v_mov_b32_e32 v141, v139
	v_pk_add_f32 v[138:139], v[142:143], v[140:141]
	v_mul_f32_e32 v140, v81, v81
	v_pk_add_f32 v[138:139], v[138:139], v[138:139] op_sel:[0,1] op_sel_hi:[1,0]
	v_mov_b32_e32 v99, v129
	v_mov_b32_e32 v139, v140
	v_pk_add_f32 v[98:99], v[98:99], v[138:139]
	v_mul_f32_e32 v138, v85, v85
	v_mul_f32_e32 v141, v82, v82
	v_pk_fma_f32 v[138:139], v[84:85], v[84:85], v[138:139] op_sel_hi:[1,1,0]
	v_mul_f32_e32 v140, v87, v87
	v_mul_f32_e32 v142, v83, v83
	v_mov_b32_e32 v139, v141
	v_pk_fma_f32 v[140:141], v[86:87], v[86:87], v[140:141] op_sel_hi:[1,1,0]
	v_pk_mul_f32 v[104:105], v[118:119], v[104:105]
	v_mov_b32_e32 v141, v142
	v_pk_add_f32 v[138:139], v[138:139], v[140:141]
	v_pk_mul_f32 v[136:137], v[112:113], v[96:97]
	v_pk_add_f32 v[98:99], v[98:99], v[138:139]
	v_or_b32_e32 v96, 16, v128
	v_add_f32_e32 v99, v98, v99
	ds_bpermute_b32 v129, v132, v99
	v_cvt_pk_bf16_f32 v98, v104, v105
	v_ashrrev_i32_e32 v97, 31, v96
	v_pk_mul_f32 v[110:111], v[126:127], v[110:111]
	v_pk_mul_f32 v[108:109], v[122:123], v[108:109]
	s_waitcnt lgkmcnt(0)
	v_add_f32_e32 v104, v99, v129
	ds_bpermute_b32 v105, v133, v104
	v_pk_mul_f32 v[106:107], v[124:125], v[106:107]
	v_lshlrev_b64 v[96:97], 10, v[96:97]
	v_lshl_add_u64 v[138:139], v[130:131], 0, v[96:97]
	v_cvt_pk_bf16_f32 v96, v108, v109
	v_cvt_pk_bf16_f32 v97, v110, v111
	v_cvt_pk_bf16_f32 v99, v106, v107
	global_store_dwordx4 v[138:139], v[96:99], off
	v_pk_mul_f32 v[100:101], v[116:117], v[100:101]
	v_pk_mul_f32 v[102:103], v[120:121], v[102:103]
	s_waitcnt lgkmcnt(0)
	v_add_f32_e32 v98, v104, v105
	v_fmamk_f32 v98, v98, 0x3c800000, v199
	v_cvt_pk_bf16_f32 v96, v100, v101
	v_rsq_f32_e32 v100, v98
	v_cvt_pk_bf16_f32 v97, v102, v103
	v_cvt_pk_bf16_f32 v98, v136, v137
	v_cvt_pk_bf16_f32 v99, v134, v135
	v_pk_mul_f32 v[82:83], v[82:83], v[100:101] op_sel_hi:[1,0]
	global_store_dwordx4 v[138:139], v[96:99], off offset:64
	v_pk_mul_f32 v[92:93], v[92:93], v[100:101] op_sel_hi:[1,0]
	v_pk_mul_f32 v[94:95], v[94:95], v[100:101] op_sel_hi:[1,0]
	v_pk_mul_f32 v[88:89], v[88:89], v[100:101] op_sel_hi:[1,0]
	v_pk_mul_f32 v[90:91], v[90:91], v[100:101] op_sel_hi:[1,0]
	v_pk_mul_f32 v[84:85], v[84:85], v[100:101] op_sel_hi:[1,0]
	v_pk_mul_f32 v[86:87], v[86:87], v[100:101] op_sel_hi:[1,0]
	v_pk_mul_f32 v[80:81], v[80:81], v[100:101] op_sel_hi:[1,0]
	v_pk_mul_f32 v[96:97], v[114:115], v[82:83]
	v_pk_mul_f32 v[82:83], v[78:79], v[78:79]
	v_pk_mul_f32 v[100:101], v[76:77], v[76:77]
	v_pk_mul_f32 v[88:89], v[118:119], v[88:89]
	v_pk_mov_b32 v[102:103], v[100:101], v[82:83] op_sel:[1,0]
	v_mov_b32_e32 v101, v83
	v_pk_add_f32 v[82:83], v[102:103], v[100:101]
	v_pk_mul_f32 v[100:101], v[74:75], v[74:75]
	v_pk_mul_f32 v[102:103], v[72:73], v[72:73]
	v_pk_add_f32 v[82:83], v[82:83], v[82:83] op_sel:[0,1] op_sel_hi:[1,0]
	v_pk_mov_b32 v[104:105], v[102:103], v[100:101] op_sel:[1,0]
	v_mov_b32_e32 v103, v101
	v_pk_add_f32 v[100:101], v[104:105], v[102:103]
	v_mul_f32_e32 v102, v64, v64
	v_mul_f32_e32 v103, v65, v65
	v_pk_add_f32 v[100:101], v[100:101], v[100:101] op_sel:[0,1] op_sel_hi:[1,0]
	v_mov_b32_e32 v83, v102
	v_mov_b32_e32 v101, v103
	v_pk_add_f32 v[82:83], v[82:83], v[100:101]
	v_mul_f32_e32 v100, v69, v69
	v_mul_f32_e32 v102, v71, v71
	v_mul_f32_e32 v104, v66, v66
	v_mul_f32_e32 v105, v67, v67
	v_pk_fma_f32 v[100:101], v[68:69], v[68:69], v[100:101] op_sel_hi:[1,1,0]
	v_pk_fma_f32 v[102:103], v[70:71], v[70:71], v[102:103] op_sel_hi:[1,1,0]
	v_mov_b32_e32 v101, v104
	v_mov_b32_e32 v103, v105
	v_pk_add_f32 v[100:101], v[100:101], v[102:103]
	v_pk_mul_f32 v[98:99], v[112:113], v[80:81]
	v_pk_add_f32 v[82:83], v[82:83], v[100:101]
	v_or_b32_e32 v80, 32, v128
	v_add_f32_e32 v83, v82, v83
	ds_bpermute_b32 v102, v132, v83
	v_cvt_pk_bf16_f32 v82, v88, v89
	v_ashrrev_i32_e32 v81, 31, v80
	v_pk_mul_f32 v[94:95], v[126:127], v[94:95]
	v_pk_mul_f32 v[92:93], v[122:123], v[92:93]
	s_waitcnt lgkmcnt(0)
; __device__ __forceinline__ unsigned cvt_pk_bf16(float lo, float hi) { const f32x2_t v = {lo, hi}; const bf16x2_t r = __builtin_convertvector(v, bf16x2_t); return __builtin_bit_cast(unsigned, r); }
;     __device__ __forceinline__ void qk(const AccT& acc, int row0, int wr, int fr, int fq, bf16_t* dst, int ld, int colh, const float* w, float scale, bool rope) const {
;     ...
;                 const int r = row0 + 128 * ai + 64 * wr + 16 * m + fr;
;                 f32x4 v[2][2]; float ss = 0.f;
; #pragma unroll
;                 for (int bj = 0; bj < 2; ++bj)
; #pragma unroll
;                     for (int n = 0; n < 2; ++n) { v[bj][n] = acc[ai][bj][m][n]; const f32x4 x = v[bj][n]; ss += (x[0] * x[0] + x[1] * x[1]) + (x[2] * x[2] + x[3] * x[3]); }
;                 ss += __shfl_xor(ss, 16); ss += __shfl_xor(ss, 32);
;                 const float inv = __builtin_amdgcn_rsqf(ss * (1.0f / 64.0f) + NORM_EPS);
; #pragma unroll
;                 for (int bj = 0; bj < 2; ++bj)
; #pragma unroll
;                     for (int n = 0; n < 2; ++n) v[bj][n] = v[bj][n] * inv * wv[bj][n];
;                 if (rope) {
;                     const float fp = (float)(r & (SEQ - 1));
; #pragma unroll
;                     for (int n = 0; n < 2; ++n) {
;                         f32x4 c, s;
; #pragma unroll
;                         for (int j = 0; j < 4; ++j) { const float fr_ = __builtin_amdgcn_fractf(fp * irev[n][j]); c[j] = __builtin_amdgcn_cosf(fr_); s[j] = __builtin_amdgcn_sinf(fr_); }
;                         const f32x4 x1 = v[0][n], x2 = v[1][n];
;                         v[0][n] = x1 * c - x2 * s; v[1][n] = x2 * c + x1 * s;
;                     }
;                 }
;                 bf16_t* rowp = dst + (size_t)r * ld + colh + 8 * fq;
; #pragma unroll
;                 for (int bj = 0; bj < 2; ++bj) { u32x4 o; o.x = cvt_pk_bf16(v[bj][0][0], v[bj][0][1]); o.y = cvt_pk_bf16(v[bj][0][2], v[bj][0][3]); o.z = cvt_pk_bf16(v[bj][1][0], v[bj][1][1]); o.w = cvt_pk_bf16(v[bj][1][2], v[bj][1][3]);
;                     *(u32x4*)(rowp + 32 * bj) = o; }
	v_add_f32_e32 v88, v83, v102
	ds_bpermute_b32 v89, v133, v88
	v_pk_mul_f32 v[90:91], v[124:125], v[90:91]
	v_lshlrev_b64 v[80:81], 10, v[80:81]
	v_lshl_add_u64 v[100:101], v[130:131], 0, v[80:81]
	v_cvt_pk_bf16_f32 v80, v92, v93
	v_cvt_pk_bf16_f32 v81, v94, v95
	v_cvt_pk_bf16_f32 v83, v90, v91
	global_store_dwordx4 v[100:101], v[80:83], off
	v_pk_mul_f32 v[84:85], v[116:117], v[84:85]
	v_pk_mul_f32 v[86:87], v[120:121], v[86:87]
	s_waitcnt lgkmcnt(0)
	v_add_f32_e32 v82, v88, v89
	v_fmamk_f32 v82, v82, 0x3c800000, v199
	v_cvt_pk_bf16_f32 v80, v84, v85
	v_rsq_f32_e32 v84, v82
	v_cvt_pk_bf16_f32 v81, v86, v87
	v_cvt_pk_bf16_f32 v82, v98, v99
	v_cvt_pk_bf16_f32 v83, v96, v97
	v_pk_mul_f32 v[64:65], v[64:65], v[84:85] op_sel_hi:[1,0]
	global_store_dwordx4 v[100:101], v[80:83], off offset:64
	v_pk_mul_f32 v[66:67], v[66:67], v[84:85] op_sel_hi:[1,0]
	v_pk_mul_f32 v[76:77], v[76:77], v[84:85] op_sel_hi:[1,0]
	v_pk_mul_f32 v[82:83], v[112:113], v[64:65]
	v_or_b32_e32 v64, 48, v128
	v_ashrrev_i32_e32 v65, 31, v64
	v_lshlrev_b64 v[64:65], 10, v[64:65]
	v_pk_mul_f32 v[78:79], v[78:79], v[84:85] op_sel_hi:[1,0]
	v_pk_mul_f32 v[72:73], v[72:73], v[84:85] op_sel_hi:[1,0]
	v_pk_mul_f32 v[74:75], v[74:75], v[84:85] op_sel_hi:[1,0]
	v_pk_mul_f32 v[68:69], v[68:69], v[84:85] op_sel_hi:[1,0]
	v_pk_mul_f32 v[70:71], v[70:71], v[84:85] op_sel_hi:[1,0]
	v_pk_mul_f32 v[80:81], v[114:115], v[66:67]
	v_lshl_add_u64 v[84:85], v[130:131], 0, v[64:65]
	v_pk_mul_f32 v[64:65], v[62:63], v[62:63]
	v_pk_mul_f32 v[66:67], v[60:61], v[60:61]
	v_pk_mul_f32 v[72:73], v[118:119], v[72:73]
	v_pk_mov_b32 v[86:87], v[66:67], v[64:65] op_sel:[1,0]
	v_mov_b32_e32 v67, v65
	v_pk_add_f32 v[64:65], v[86:87], v[66:67]
	v_pk_mul_f32 v[66:67], v[58:59], v[58:59]
	v_pk_mul_f32 v[86:87], v[56:57], v[56:57]
	v_pk_add_f32 v[64:65], v[64:65], v[64:65] op_sel:[0,1] op_sel_hi:[1,0]
	v_pk_mov_b32 v[88:89], v[86:87], v[66:67] op_sel:[1,0]
	v_mov_b32_e32 v87, v67
	v_pk_add_f32 v[66:67], v[88:89], v[86:87]
	v_mul_f32_e32 v86, v48, v48
	v_mul_f32_e32 v87, v49, v49
	v_pk_add_f32 v[66:67], v[66:67], v[66:67] op_sel:[0,1] op_sel_hi:[1,0]
	v_mov_b32_e32 v65, v86
	v_mov_b32_e32 v67, v87
	v_pk_add_f32 v[64:65], v[64:65], v[66:67]
	v_mul_f32_e32 v66, v53, v53
	v_mul_f32_e32 v86, v55, v55
	v_mul_f32_e32 v88, v50, v50
	v_mul_f32_e32 v89, v51, v51
	v_pk_fma_f32 v[66:67], v[52:53], v[52:53], v[66:67] op_sel_hi:[1,1,0]
	v_pk_fma_f32 v[86:87], v[54:55], v[54:55], v[86:87] op_sel_hi:[1,1,0]
	v_mov_b32_e32 v67, v88
	v_mov_b32_e32 v87, v89
	v_pk_add_f32 v[66:67], v[66:67], v[86:87]
	v_pk_mul_f32 v[78:79], v[126:127], v[78:79]
	v_pk_add_f32 v[64:65], v[64:65], v[66:67]
	v_cvt_pk_bf16_f32 v66, v72, v73
	v_add_f32_e32 v86, v64, v65
	ds_bpermute_b32 v87, v132, v86
	v_pk_mul_f32 v[76:77], v[122:123], v[76:77]
	v_pk_mul_f32 v[74:75], v[124:125], v[74:75]
	v_cvt_pk_bf16_f32 v64, v76, v77
	v_cvt_pk_bf16_f32 v65, v78, v79
	s_waitcnt lgkmcnt(0)
	v_add_f32_e32 v72, v86, v87
	ds_bpermute_b32 v73, v133, v72
	v_cvt_pk_bf16_f32 v67, v74, v75
	global_store_dwordx4 v[84:85], v[64:67], off
	v_pk_mul_f32 v[68:69], v[116:117], v[68:69]
	v_pk_mul_f32 v[70:71], v[120:121], v[70:71]
	s_waitcnt lgkmcnt(0)
	v_add_f32_e32 v67, v72, v73
	v_fmamk_f32 v67, v67, 0x3c800000, v199
	v_cvt_pk_bf16_f32 v64, v68, v69
	v_rsq_f32_e32 v68, v67
	v_cvt_pk_bf16_f32 v65, v70, v71
	v_cvt_pk_bf16_f32 v66, v82, v83
	v_cvt_pk_bf16_f32 v67, v80, v81
	global_store_dwordx4 v[84:85], v[64:67], off offset:64
	v_pk_mul_f32 v[48:49], v[48:49], v[68:69] op_sel_hi:[1,0]
	v_pk_mul_f32 v[50:51], v[50:51], v[68:69] op_sel_hi:[1,0]
	v_add_u32_e32 v64, 0x80, v128
	v_ashrrev_i32_e32 v65, 31, v64
	v_pk_mul_f32 v[60:61], v[60:61], v[68:69] op_sel_hi:[1,0]
	v_pk_mul_f32 v[62:63], v[62:63], v[68:69] op_sel_hi:[1,0]
	v_pk_mul_f32 v[56:57], v[56:57], v[68:69] op_sel_hi:[1,0]
	v_pk_mul_f32 v[58:59], v[58:59], v[68:69] op_sel_hi:[1,0]
	v_pk_mul_f32 v[52:53], v[52:53], v[68:69] op_sel_hi:[1,0]
	v_pk_mul_f32 v[54:55], v[54:55], v[68:69] op_sel_hi:[1,0]
	v_pk_mul_f32 v[66:67], v[114:115], v[50:51]
	v_pk_mul_f32 v[68:69], v[112:113], v[48:49]
	v_lshlrev_b64 v[48:49], 10, v[64:65]
	v_pk_mul_f32 v[50:51], v[46:47], v[46:47]
	v_pk_mul_f32 v[64:65], v[44:45], v[44:45]
	v_pk_mul_f32 v[56:57], v[118:119], v[56:57]
	v_pk_mov_b32 v[70:71], v[64:65], v[50:51] op_sel:[1,0]
	v_mov_b32_e32 v65, v51
	v_pk_add_f32 v[50:51], v[70:71], v[64:65]
	v_pk_mul_f32 v[64:65], v[42:43], v[42:43]
	v_pk_mul_f32 v[70:71], v[40:41], v[40:41]
	v_pk_add_f32 v[50:51], v[50:51], v[50:51] op_sel:[0,1] op_sel_hi:[1,0]
	v_pk_mov_b32 v[72:73], v[70:71], v[64:65] op_sel:[1,0]
	v_mov_b32_e32 v71, v65
	v_pk_add_f32 v[64:65], v[72:73], v[70:71]
	v_mul_f32_e32 v70, v32, v32
	v_mul_f32_e32 v71, v33, v33
	v_pk_add_f32 v[64:65], v[64:65], v[64:65] op_sel:[0,1] op_sel_hi:[1,0]
	v_mov_b32_e32 v51, v70
	v_mov_b32_e32 v65, v71
	v_pk_add_f32 v[50:51], v[50:51], v[64:65]
	v_mul_f32_e32 v64, v37, v37
	v_mul_f32_e32 v70, v39, v39
	v_mul_f32_e32 v72, v34, v34
	v_mul_f32_e32 v73, v35, v35
	v_pk_fma_f32 v[64:65], v[36:37], v[36:37], v[64:65] op_sel_hi:[1,1,0]
	v_pk_fma_f32 v[70:71], v[38:39], v[38:39], v[70:71] op_sel_hi:[1,1,0]
	v_mov_b32_e32 v65, v72
	v_mov_b32_e32 v71, v73
	v_pk_add_f32 v[64:65], v[64:65], v[70:71]
	v_pk_mul_f32 v[62:63], v[126:127], v[62:63]
	v_pk_add_f32 v[50:51], v[50:51], v[64:65]
	v_pk_mul_f32 v[60:61], v[122:123], v[60:61]
	v_add_f32_e32 v51, v50, v51
	ds_bpermute_b32 v70, v132, v51
	v_cvt_pk_bf16_f32 v50, v56, v57
	v_pk_mul_f32 v[58:59], v[124:125], v[58:59]
	v_lshl_add_u64 v[64:65], v[130:131], 0, v[48:49]
	v_cvt_pk_bf16_f32 v48, v60, v61
	s_waitcnt lgkmcnt(0)
; __device__ __forceinline__ unsigned cvt_pk_bf16(float lo, float hi) { const f32x2_t v = {lo, hi}; const bf16x2_t r = __builtin_convertvector(v, bf16x2_t); return __builtin_bit_cast(unsigned, r); }
;     __device__ __forceinline__ void qk(const AccT& acc, int row0, int wr, int fr, int fq, bf16_t* dst, int ld, int colh, const float* w, float scale, bool rope) const {
;     ...
;                 const int r = row0 + 128 * ai + 64 * wr + 16 * m + fr;
;                 f32x4 v[2][2]; float ss = 0.f;
; #pragma unroll
;                 for (int bj = 0; bj < 2; ++bj)
; #pragma unroll
;                     for (int n = 0; n < 2; ++n) { v[bj][n] = acc[ai][bj][m][n]; const f32x4 x = v[bj][n]; ss += (x[0] * x[0] + x[1] * x[1]) + (x[2] * x[2] + x[3] * x[3]); }
;                 ss += __shfl_xor(ss, 16); ss += __shfl_xor(ss, 32);
;                 const float inv = __builtin_amdgcn_rsqf(ss * (1.0f / 64.0f) + NORM_EPS);
; #pragma unroll
;                 for (int bj = 0; bj < 2; ++bj)
; #pragma unroll
;                     for (int n = 0; n < 2; ++n) v[bj][n] = v[bj][n] * inv * wv[bj][n];
;                 if (rope) {
;                     const float fp = (float)(r & (SEQ - 1));
; #pragma unroll
;                     for (int n = 0; n < 2; ++n) {
;                         f32x4 c, s;
; #pragma unroll
;                         for (int j = 0; j < 4; ++j) { const float fr_ = __builtin_amdgcn_fractf(fp * irev[n][j]); c[j] = __builtin_amdgcn_cosf(fr_); s[j] = __builtin_amdgcn_sinf(fr_); }
;                         const f32x4 x1 = v[0][n], x2 = v[1][n];
;                         v[0][n] = x1 * c - x2 * s; v[1][n] = x2 * c + x1 * s;
;                     }
;                 }
;                 bf16_t* rowp = dst + (size_t)r * ld + colh + 8 * fq;
; #pragma unroll
;                 for (int bj = 0; bj < 2; ++bj) { u32x4 o; o.x = cvt_pk_bf16(v[bj][0][0], v[bj][0][1]); o.y = cvt_pk_bf16(v[bj][0][2], v[bj][0][3]); o.z = cvt_pk_bf16(v[bj][1][0], v[bj][1][1]); o.w = cvt_pk_bf16(v[bj][1][2], v[bj][1][3]);
;                     *(u32x4*)(rowp + 32 * bj) = o; }
	v_add_f32_e32 v56, v51, v70
	ds_bpermute_b32 v57, v133, v56
	v_cvt_pk_bf16_f32 v49, v62, v63
	v_cvt_pk_bf16_f32 v51, v58, v59
	global_store_dwordx4 v[64:65], v[48:51], off
	v_pk_mul_f32 v[52:53], v[116:117], v[52:53]
	v_pk_mul_f32 v[54:55], v[120:121], v[54:55]
	s_waitcnt lgkmcnt(0)
	v_add_f32_e32 v50, v56, v57
	v_fmamk_f32 v50, v50, 0x3c800000, v199
	v_cvt_pk_bf16_f32 v48, v52, v53
	v_rsq_f32_e32 v52, v50
	v_cvt_pk_bf16_f32 v49, v54, v55
	v_cvt_pk_bf16_f32 v50, v68, v69
	v_cvt_pk_bf16_f32 v51, v66, v67
	v_pk_mul_f32 v[34:35], v[34:35], v[52:53] op_sel_hi:[1,0]
	global_store_dwordx4 v[64:65], v[48:51], off offset:64
	v_pk_mul_f32 v[44:45], v[44:45], v[52:53] op_sel_hi:[1,0]
	v_pk_mul_f32 v[46:47], v[46:47], v[52:53] op_sel_hi:[1,0]
	v_pk_mul_f32 v[40:41], v[40:41], v[52:53] op_sel_hi:[1,0]
	v_pk_mul_f32 v[42:43], v[42:43], v[52:53] op_sel_hi:[1,0]
	v_pk_mul_f32 v[36:37], v[36:37], v[52:53] op_sel_hi:[1,0]
	v_pk_mul_f32 v[38:39], v[38:39], v[52:53] op_sel_hi:[1,0]
	v_pk_mul_f32 v[32:33], v[32:33], v[52:53] op_sel_hi:[1,0]
	v_pk_mul_f32 v[48:49], v[114:115], v[34:35]
	v_pk_mul_f32 v[34:35], v[30:31], v[30:31]
	v_pk_mul_f32 v[52:53], v[28:29], v[28:29]
	v_pk_mul_f32 v[40:41], v[118:119], v[40:41]
	v_pk_mov_b32 v[54:55], v[52:53], v[34:35] op_sel:[1,0]
	v_mov_b32_e32 v53, v35
	v_pk_add_f32 v[34:35], v[54:55], v[52:53]
	v_pk_mul_f32 v[52:53], v[26:27], v[26:27]
	v_pk_mul_f32 v[54:55], v[24:25], v[24:25]
	v_pk_add_f32 v[34:35], v[34:35], v[34:35] op_sel:[0,1] op_sel_hi:[1,0]
	v_pk_mov_b32 v[56:57], v[54:55], v[52:53] op_sel:[1,0]
	v_mov_b32_e32 v55, v53
	v_pk_add_f32 v[52:53], v[56:57], v[54:55]
	v_mul_f32_e32 v54, v16, v16
	v_mul_f32_e32 v55, v17, v17
	v_pk_add_f32 v[52:53], v[52:53], v[52:53] op_sel:[0,1] op_sel_hi:[1,0]
	v_mov_b32_e32 v35, v54
	v_mov_b32_e32 v53, v55
	v_pk_add_f32 v[34:35], v[34:35], v[52:53]
	v_mul_f32_e32 v52, v21, v21
	v_mul_f32_e32 v54, v23, v23
	v_mul_f32_e32 v56, v18, v18
	v_mul_f32_e32 v57, v19, v19
	v_pk_fma_f32 v[52:53], v[20:21], v[20:21], v[52:53] op_sel_hi:[1,1,0]
	v_pk_fma_f32 v[54:55], v[22:23], v[22:23], v[54:55] op_sel_hi:[1,1,0]
	v_mov_b32_e32 v53, v56
	v_mov_b32_e32 v55, v57
	v_pk_add_f32 v[52:53], v[52:53], v[54:55]
	v_pk_mul_f32 v[50:51], v[112:113], v[32:33]
	v_pk_add_f32 v[34:35], v[34:35], v[52:53]
	v_add_u32_e32 v32, 0x90, v128
	v_add_f32_e32 v35, v34, v35
	ds_bpermute_b32 v54, v132, v35
	v_cvt_pk_bf16_f32 v34, v40, v41
	v_ashrrev_i32_e32 v33, 31, v32
	v_pk_mul_f32 v[46:47], v[126:127], v[46:47]
	v_pk_mul_f32 v[44:45], v[122:123], v[44:45]
	s_waitcnt lgkmcnt(0)
	v_add_f32_e32 v40, v35, v54
	ds_bpermute_b32 v41, v133, v40
	v_pk_mul_f32 v[42:43], v[124:125], v[42:43]
	v_lshlrev_b64 v[32:33], 10, v[32:33]
	v_lshl_add_u64 v[52:53], v[130:131], 0, v[32:33]
	v_cvt_pk_bf16_f32 v32, v44, v45
	v_cvt_pk_bf16_f32 v33, v46, v47
	v_cvt_pk_bf16_f32 v35, v42, v43
	global_store_dwordx4 v[52:53], v[32:35], off
	v_pk_mul_f32 v[36:37], v[116:117], v[36:37]
	v_pk_mul_f32 v[38:39], v[120:121], v[38:39]
	s_waitcnt lgkmcnt(0)
	v_add_f32_e32 v34, v40, v41
	v_fmamk_f32 v34, v34, 0x3c800000, v199
	v_cvt_pk_bf16_f32 v32, v36, v37
	v_rsq_f32_e32 v36, v34
	v_cvt_pk_bf16_f32 v33, v38, v39
	v_cvt_pk_bf16_f32 v34, v50, v51
	v_cvt_pk_bf16_f32 v35, v48, v49
	v_pk_mul_f32 v[18:19], v[18:19], v[36:37] op_sel_hi:[1,0]
	global_store_dwordx4 v[52:53], v[32:35], off offset:64
	v_pk_mul_f32 v[28:29], v[28:29], v[36:37] op_sel_hi:[1,0]
	v_pk_mul_f32 v[30:31], v[30:31], v[36:37] op_sel_hi:[1,0]
	v_pk_mul_f32 v[24:25], v[24:25], v[36:37] op_sel_hi:[1,0]
	v_pk_mul_f32 v[26:27], v[26:27], v[36:37] op_sel_hi:[1,0]
	v_pk_mul_f32 v[20:21], v[20:21], v[36:37] op_sel_hi:[1,0]
	v_pk_mul_f32 v[22:23], v[22:23], v[36:37] op_sel_hi:[1,0]
	v_pk_mul_f32 v[16:17], v[16:17], v[36:37] op_sel_hi:[1,0]
	v_pk_mul_f32 v[32:33], v[114:115], v[18:19]
	v_pk_mul_f32 v[18:19], v[14:15], v[14:15]
	v_pk_mul_f32 v[36:37], v[12:13], v[12:13]
	v_pk_mul_f32 v[24:25], v[118:119], v[24:25]
	v_pk_mov_b32 v[38:39], v[36:37], v[18:19] op_sel:[1,0]
	v_mov_b32_e32 v37, v19
	v_pk_add_f32 v[18:19], v[38:39], v[36:37]
	v_pk_mul_f32 v[36:37], v[10:11], v[10:11]
	v_pk_mul_f32 v[38:39], v[8:9], v[8:9]
	v_pk_add_f32 v[18:19], v[18:19], v[18:19] op_sel:[0,1] op_sel_hi:[1,0]
	v_pk_mov_b32 v[40:41], v[38:39], v[36:37] op_sel:[1,0]
	v_mov_b32_e32 v39, v37
	v_pk_add_f32 v[36:37], v[40:41], v[38:39]
	v_mul_f32_e32 v38, v0, v0
	v_mul_f32_e32 v39, v1, v1
	v_pk_add_f32 v[36:37], v[36:37], v[36:37] op_sel:[0,1] op_sel_hi:[1,0]
	v_mov_b32_e32 v19, v38
	v_mov_b32_e32 v37, v39
	v_pk_add_f32 v[18:19], v[18:19], v[36:37]
	v_mul_f32_e32 v36, v5, v5
	v_mul_f32_e32 v38, v7, v7
	v_mul_f32_e32 v40, v2, v2
	v_mul_f32_e32 v41, v3, v3
	v_pk_fma_f32 v[36:37], v[4:5], v[4:5], v[36:37] op_sel_hi:[1,1,0]
	v_pk_fma_f32 v[38:39], v[6:7], v[6:7], v[38:39] op_sel_hi:[1,1,0]
	v_mov_b32_e32 v37, v40
	v_mov_b32_e32 v39, v41
	v_pk_add_f32 v[36:37], v[36:37], v[38:39]
	v_pk_mul_f32 v[34:35], v[112:113], v[16:17]
	v_pk_add_f32 v[18:19], v[18:19], v[36:37]
	v_add_u32_e32 v16, 0xa0, v128
	v_add_f32_e32 v19, v18, v19
	ds_bpermute_b32 v38, v132, v19
	v_cvt_pk_bf16_f32 v18, v24, v25
	v_ashrrev_i32_e32 v17, 31, v16
	v_pk_mul_f32 v[30:31], v[126:127], v[30:31]
	v_pk_mul_f32 v[28:29], v[122:123], v[28:29]
	s_waitcnt lgkmcnt(0)
; __device__ __forceinline__ unsigned cvt_pk_bf16(float lo, float hi) { const f32x2_t v = {lo, hi}; const bf16x2_t r = __builtin_convertvector(v, bf16x2_t); return __builtin_bit_cast(unsigned, r); }
;     __device__ __forceinline__ void qk(const AccT& acc, int row0, int wr, int fr, int fq, bf16_t* dst, int ld, int colh, const float* w, float scale, bool rope) const {
;     ...
;                 bf16_t* rowp = dst + (size_t)r * ld + colh + 8 * fq;
; #pragma unroll
;                 for (int bj = 0; bj < 2; ++bj) { u32x4 o; o.x = cvt_pk_bf16(v[bj][0][0], v[bj][0][1]); o.y = cvt_pk_bf16(v[bj][0][2], v[bj][0][3]); o.z = cvt_pk_bf16(v[bj][1][0], v[bj][1][1]); o.w = cvt_pk_bf16(v[bj][1][2], v[bj][1][3]);
;                     *(u32x4*)(rowp + 32 * bj) = o; }
; __device__ __forceinline__ void p0_load4(const Args& a, int m0, int NGW, int lane, f32x4 (&v)[4][4]) {
; #pragma unroll
;     for (int u = 0; u < 4; ++u) { const int m = min(m0 + u * NGW, T - 1);
;         const float* xrow = m < TP ? a.in[0] + (size_t)m * 1024 : a.in[1] + (size_t)(m - TP) * 1024;
;         const f32x4* xr = (const f32x4*)xrow + lane;
; #pragma unroll
;         for (int j = 0; j < 4; ++j) v[u][j] = xr[64 * j]; }
	v_add_f32_e32 v24, v19, v38
	ds_bpermute_b32 v25, v133, v24
	v_pk_mul_f32 v[26:27], v[124:125], v[26:27]
	v_lshlrev_b64 v[16:17], 10, v[16:17]
	v_lshl_add_u64 v[36:37], v[130:131], 0, v[16:17]
	v_cvt_pk_bf16_f32 v16, v28, v29
	v_cvt_pk_bf16_f32 v17, v30, v31
	v_cvt_pk_bf16_f32 v19, v26, v27
	global_store_dwordx4 v[36:37], v[16:19], off
	v_pk_mul_f32 v[20:21], v[116:117], v[20:21]
	v_pk_mul_f32 v[22:23], v[120:121], v[22:23]
	s_waitcnt lgkmcnt(0)
	v_add_f32_e32 v18, v24, v25
	v_fmamk_f32 v18, v18, 0x3c800000, v199
	v_cvt_pk_bf16_f32 v16, v20, v21
	v_rsq_f32_e32 v20, v18
	v_cvt_pk_bf16_f32 v17, v22, v23
	v_cvt_pk_bf16_f32 v18, v34, v35
	v_cvt_pk_bf16_f32 v19, v32, v33
	v_pk_mul_f32 v[0:1], v[0:1], v[20:21] op_sel_hi:[1,0]
	global_store_dwordx4 v[36:37], v[16:19], off offset:64
	v_pk_mul_f32 v[12:13], v[12:13], v[20:21] op_sel_hi:[1,0]
	v_pk_mul_f32 v[14:15], v[14:15], v[20:21] op_sel_hi:[1,0]
	v_pk_mul_f32 v[18:19], v[112:113], v[0:1]
	v_add_u32_e32 v0, 0xb0, v128
	v_pk_mul_f32 v[8:9], v[8:9], v[20:21] op_sel_hi:[1,0]
	v_pk_mul_f32 v[10:11], v[10:11], v[20:21] op_sel_hi:[1,0]
	v_ashrrev_i32_e32 v1, 31, v0
	v_pk_mul_f32 v[14:15], v[126:127], v[14:15]
	v_pk_mul_f32 v[12:13], v[122:123], v[12:13]
	v_pk_mul_f32 v[10:11], v[124:125], v[10:11]
	v_pk_mul_f32 v[8:9], v[118:119], v[8:9]
	v_pk_mul_f32 v[4:5], v[4:5], v[20:21] op_sel_hi:[1,0]
	v_pk_mul_f32 v[6:7], v[6:7], v[20:21] op_sel_hi:[1,0]
	v_pk_mul_f32 v[2:3], v[2:3], v[20:21] op_sel_hi:[1,0]
	v_lshlrev_b64 v[0:1], 10, v[0:1]
	v_pk_mul_f32 v[6:7], v[120:121], v[6:7]
	v_pk_mul_f32 v[4:5], v[116:117], v[4:5]
	v_pk_mul_f32 v[16:17], v[114:115], v[2:3]
	v_lshl_add_u64 v[20:21], v[130:131], 0, v[0:1]
	v_cvt_pk_bf16_f32 v0, v12, v13
	v_cvt_pk_bf16_f32 v1, v14, v15
	v_cvt_pk_bf16_f32 v2, v8, v9
	v_cvt_pk_bf16_f32 v3, v10, v11
	global_store_dwordx4 v[20:21], v[0:3], off
	s_nop 1
	v_cvt_pk_bf16_f32 v0, v4, v5
	v_cvt_pk_bf16_f32 v1, v6, v7
	v_cvt_pk_bf16_f32 v2, v18, v19
	v_cvt_pk_bf16_f32 v3, v16, v17
	global_store_dwordx4 v[20:21], v[0:3], off offset:64
	s_branch .LBB0_208
.LBB0_179:
	s_cmp_lt_i32 s99, 0
	s_cbranch_scc1 .Lax_nosig_a
	v_readfirstlane_b32 s100, v190
	s_nop 0
	s_cmp_lt_u32 s100, 64
	s_cbranch_scc0 .Lax_sigdone_a
	s_lshl_b32 s100, s99, 4
	s_add_u32 s100, s100, s92
	s_addc_u32 s101, s93, 0
	s_add_u32 s100, s100, 0x3800
	s_addc_u32 s101, s101, 0
	v_mov_b32_e32 v254, 0
	v_mov_b32_e32 v255, 1
	s_mov_b64 exec, 1
	global_atomic_add v254, v255, s[100:101]
	s_mov_b64 exec, -1
.Lax_sigdone_a:
	s_mov_b32 s99, -1
.Lax_nosig_a:
	s_lshr_b32 s100, s8, 5
	s_add_i32 s100, s100, 1
	s_cmp_lt_u32 s100, 2
	s_cbranch_scc1 .Lax_noep
	s_cmp_gt_u32 s100, 5
	s_cbranch_scc1 .Lax_noep
	v_readfirstlane_b32 s101, v190
	s_nop 0
	s_cmp_lt_u32 s101, 64
	s_cbranch_scc0 .Lax_noep
	s_and_b32 s101, s8, 7
	s_lshl_b32 s101, s101, 3
	s_add_i32 s100, s100, s101
	s_lshl_b32 s100, s100, 4
	s_add_u32 s100, s100, s92
	s_addc_u32 s101, s93, 0
	s_add_u32 s100, s100, 0x3800
	s_addc_u32 s101, s101, 0
	v_mov_b32_e32 v254, 0
	global_load_dword v248, v254, s[100:101] sc1
.Lax_noep:
	s_lshr_b32 s100, s8, 5
	s_bfe_u32 s98, s8, 0x20003
	s_lshl_b32 s101, s38, 2
	s_add_i32 s98, s98, s101
	s_cmp_lt_u32 s100, 4
	s_cselect_b32 s101, s98, 64
	s_cmp_lt_u32 s101, 64
	s_cbranch_scc0 .Lax_noduty
	s_lshl_b32 s100, s100, 2
	s_lshr_b32 s101, s98, 4
	s_add_i32 s100, s100, s101
	s_add_i32 s100, s100, 8
	s_lshl_b32 s100, s100, 3
	s_and_b32 s101, s8, 7
	s_or_b32 s100, s100, s101
	s_lshl_b32 s100, s100, 8
	s_and_b32 s101, s98, 15
	s_lshl_b32 s101, s101, 4
	s_add_i32 s98, s100, s101
	v_readfirstlane_b32 s100, v190
	v_and_b32_e32 v254, 63, v190
	v_lshrrev_b32_e32 v255, 6, v190
	s_lshr_b32 s100, s100, 5
	s_add_i32 s98, s98, s100
	s_cmp_lt_u32 s98, 0x8000
	s_cselect_b32 s100, s76, s78
	s_cselect_b32 s101, s77, s79
	s_cselect_b32 vcc_lo, 0, 0x8000
	s_sub_u32 vcc_lo, s98, vcc_lo
	s_lshl_b32 vcc_lo, vcc_lo, 12
	s_add_u32 s100, s100, vcc_lo
	s_addc_u32 s101, s101, 0
	v_lshlrev_b32_e32 v254, 4, v254
	v_lshlrev_b32_e32 v255, 11, v255
	v_add_u32_e32 v255, v255, v254
	v_add_u32_e32 v255, 0x20000, v255
	s_and_b32 s99, s8, 7
	s_lshl_b32 s99, s99, 3
	s_lshr_b32 vcc_lo, s8, 5
	s_add_i32 s99, s99, vcc_lo
	s_add_i32 s99, s99, 2
	ds_write_b128 v255, v[178:181]
	ds_write_b128 v255, v[154:157] offset:1024
	global_load_dwordx4 v[232:235], v254, s[100:101]
	global_load_dwordx4 v[236:239], v254, s[100:101] offset:1024
	global_load_dwordx4 v[240:243], v254, s[100:101] offset:2048
	global_load_dwordx4 v[244:247], v254, s[100:101] offset:3072
	s_add_u32 s100, s100, 0x1000
	s_addc_u32 s101, s101, 0
	global_load_dwordx4 v[182:185], v254, s[100:101]
	global_load_dwordx4 v[250:253], v254, s[100:101] offset:1024
	global_load_dwordx4 v[178:181], v254, s[100:101] offset:2048
	global_load_dwordx4 v[154:157], v254, s[100:101] offset:3072
	s_branch .Lax_issued
.Lax_noduty:
	s_mov_b32 s98, -1

; __device__ __forceinline__ unsigned cvt_pk_bf16(float lo, float hi) { const f32x2_t v = {lo, hi}; const bf16x2_t r = __builtin_convertvector(v, bf16x2_t); return __builtin_bit_cast(unsigned, r); }
; __device__ __forceinline__ void p0_proc4(bf16_t* XB, int m0, int NGW, int lane, const f32x4 (&v)[4][4]) {
;     float s[4];
; #pragma unroll
;     for (int u = 0; u < 4; ++u) { float t = 0.f;
; #pragma unroll
;         for (int j = 0; j < 4; ++j) t += (v[u][j][0] * v[u][j][0] + v[u][j][1] * v[u][j][1]) + (v[u][j][2] * v[u][j][2] + v[u][j][3] * v[u][j][3]);
;         s[u] = t; }
; #pragma unroll
;     for (int o = 1; o < 64; o <<= 1) {
; #pragma unroll
;         for (int u = 0; u < 4; ++u) s[u] += __shfl_xor(s[u], o); }
; #pragma unroll
;     for (int u = 0; u < 4; ++u) { const int m = m0 + u * NGW; if (m >= T) break;
;         const float rstd = 1.0f / sqrtf(s[u] * (1.0f / 1024.0f) + NORM_EPS);
;         u32x2* o8 = (u32x2*)(XB + (size_t)m * 1024) + lane;
; #pragma unroll
;         for (int j = 0; j < 4; ++j) { u32x2 w; w.x = cvt_pk_bf16(v[u][j][0] * rstd, v[u][j][1] * rstd); w.y = cvt_pk_bf16(v[u][j][2] * rstd, v[u][j][3] * rstd); o8[64 * j] = w; } }
.LBB0_208:
	s_cmp_eq_u32 s98, -1
	s_cbranch_scc1 .Lax_done
	s_waitcnt vmcnt(16)
	v_mul_f32_e32 v203, v232, v232
	v_mul_f32_e32 v204, v234, v234
	v_fmac_f32_e32 v203, v233, v233
	v_fmac_f32_e32 v204, v235, v235
	v_add_f32_e32 v203, v203, v204
	v_mov_b32_e32 v201, v203
	v_mul_f32_e32 v203, v236, v236
	v_mul_f32_e32 v204, v238, v238
	v_fmac_f32_e32 v203, v237, v237
	v_fmac_f32_e32 v204, v239, v239
	v_add_f32_e32 v203, v203, v204
	v_add_f32_e32 v201, v201, v203
	v_mul_f32_e32 v203, v240, v240
	v_mul_f32_e32 v204, v242, v242
	v_fmac_f32_e32 v203, v241, v241
	v_fmac_f32_e32 v204, v243, v243
	v_add_f32_e32 v203, v203, v204
	v_add_f32_e32 v201, v201, v203
	v_mul_f32_e32 v203, v244, v244
	v_mul_f32_e32 v204, v246, v246
	v_fmac_f32_e32 v203, v245, v245
	v_fmac_f32_e32 v204, v247, v247
	v_add_f32_e32 v203, v203, v204
	v_add_f32_e32 v201, v201, v203
	v_mul_f32_e32 v205, v182, v182
	v_mul_f32_e32 v206, v184, v184
	v_fmac_f32_e32 v205, v183, v183
	v_fmac_f32_e32 v206, v185, v185
	v_add_f32_e32 v205, v205, v206
	v_mov_b32_e32 v202, v205
	v_mul_f32_e32 v205, v250, v250
	v_mul_f32_e32 v206, v252, v252
	v_fmac_f32_e32 v205, v251, v251
	v_fmac_f32_e32 v206, v253, v253
	v_add_f32_e32 v205, v205, v206
	v_add_f32_e32 v202, v202, v205
	v_mul_f32_e32 v205, v178, v178
	v_mul_f32_e32 v206, v180, v180
	v_fmac_f32_e32 v205, v179, v179
	v_fmac_f32_e32 v206, v181, v181
	v_add_f32_e32 v205, v205, v206
	v_add_f32_e32 v202, v202, v205
	v_mul_f32_e32 v205, v154, v154
	v_mul_f32_e32 v206, v156, v156
	v_fmac_f32_e32 v205, v155, v155
	v_fmac_f32_e32 v206, v157, v157
	v_add_f32_e32 v205, v205, v206
	v_add_f32_e32 v202, v202, v205
	v_lshrrev_b32_e32 v210, 2, v254
	v_xor_b32_e32 v211, 4, v210
	ds_bpermute_b32 v207, v211, v201
	ds_bpermute_b32 v208, v211, v202
	s_waitcnt lgkmcnt(0)
	v_add_f32_e32 v201, v201, v207
	v_add_f32_e32 v202, v202, v208
	v_xor_b32_e32 v211, 8, v210
	ds_bpermute_b32 v207, v211, v201
	ds_bpermute_b32 v208, v211, v202
	s_waitcnt lgkmcnt(0)
	v_add_f32_e32 v201, v201, v207
	v_add_f32_e32 v202, v202, v208
	v_xor_b32_e32 v211, 16, v210
	ds_bpermute_b32 v207, v211, v201
	ds_bpermute_b32 v208, v211, v202
	s_waitcnt lgkmcnt(0)
	v_add_f32_e32 v201, v201, v207
	v_add_f32_e32 v202, v202, v208
	v_xor_b32_e32 v211, 32, v210
	ds_bpermute_b32 v207, v211, v201
	ds_bpermute_b32 v208, v211, v202
	s_waitcnt lgkmcnt(0)
	v_add_f32_e32 v201, v201, v207
	v_add_f32_e32 v202, v202, v208
	v_xor_b32_e32 v211, 64, v210
	ds_bpermute_b32 v207, v211, v201
	ds_bpermute_b32 v208, v211, v202
	s_waitcnt lgkmcnt(0)
	v_add_f32_e32 v201, v201, v207
	v_add_f32_e32 v202, v202, v208
	v_xor_b32_e32 v211, 128, v210
	ds_bpermute_b32 v207, v211, v201
	ds_bpermute_b32 v208, v211, v202
	s_waitcnt lgkmcnt(0)
	v_add_f32_e32 v201, v201, v207
	v_add_f32_e32 v202, v202, v208
	v_mov_b32_e32 v212, 0x358637bd
	s_nop 0
	v_fmamk_f32 v213, v201, 0x3a800000, v212
	v_fmamk_f32 v214, v202, 0x3a800000, v212
	v_rsq_f32_e32 v215, v213
	v_rsq_f32_e32 v216, v214
	s_nop 0
	v_mul_f32_e32 v217, v213, v215
	v_mul_f32_e32 v218, v214, v216
	v_fma_f32 v217, -v217, v215, 1.0
	v_fma_f32 v218, -v218, v216, 1.0
	v_mul_f32_e32 v219, 0.5, v215
	v_mul_f32_e32 v220, 0.5, v216
	v_fma_f32 v222, v219, v217, v215
	v_fma_f32 v224, v220, v218, v216
	s_lshl_b32 s100, s98, 11
	s_add_u32 s100, s100, s64
	s_addc_u32 s101, s65, 0
	s_add_u32 s100, s100, 0x1100000
	s_addc_u32 s101, s101, 0
	v_lshrrev_b32_e32 v221, 1, v254
	v_pk_mul_f32 v[226:227], v[232:233], v[222:223] op_sel_hi:[1,0]
	v_pk_mul_f32 v[228:229], v[234:235], v[222:223] op_sel_hi:[1,0]
	v_cvt_pk_bf16_f32 v230, v226, v227
	v_cvt_pk_bf16_f32 v231, v228, v229
	global_store_dwordx2 v221, v[230:231], s[100:101] offset:0
	v_pk_mul_f32 v[226:227], v[236:237], v[222:223] op_sel_hi:[1,0]
	v_pk_mul_f32 v[228:229], v[238:239], v[222:223] op_sel_hi:[1,0]
	v_cvt_pk_bf16_f32 v202, v226, v227
	v_cvt_pk_bf16_f32 v203, v228, v229
	global_store_dwordx2 v221, v[202:203], s[100:101] offset:512
	v_pk_mul_f32 v[226:227], v[240:241], v[222:223] op_sel_hi:[1,0]
	v_pk_mul_f32 v[228:229], v[242:243], v[222:223] op_sel_hi:[1,0]
	v_cvt_pk_bf16_f32 v230, v226, v227
	v_cvt_pk_bf16_f32 v231, v228, v229
	global_store_dwordx2 v221, v[230:231], s[100:101] offset:1024
	v_pk_mul_f32 v[226:227], v[244:245], v[222:223] op_sel_hi:[1,0]
	v_pk_mul_f32 v[228:229], v[246:247], v[222:223] op_sel_hi:[1,0]
	v_cvt_pk_bf16_f32 v202, v226, v227
	v_cvt_pk_bf16_f32 v203, v228, v229
	global_store_dwordx2 v221, v[202:203], s[100:101] offset:1536
	v_pk_mul_f32 v[226:227], v[182:183], v[224:225] op_sel_hi:[1,0]
	v_pk_mul_f32 v[228:229], v[184:185], v[224:225] op_sel_hi:[1,0]
	v_cvt_pk_bf16_f32 v230, v226, v227
	v_cvt_pk_bf16_f32 v231, v228, v229
	global_store_dwordx2 v221, v[230:231], s[100:101] offset:2048
	v_pk_mul_f32 v[226:227], v[250:251], v[224:225] op_sel_hi:[1,0]
	v_pk_mul_f32 v[228:229], v[252:253], v[224:225] op_sel_hi:[1,0]
	v_cvt_pk_bf16_f32 v202, v226, v227
	v_cvt_pk_bf16_f32 v203, v228, v229
	global_store_dwordx2 v221, v[202:203], s[100:101] offset:2560
	v_pk_mul_f32 v[226:227], v[178:179], v[224:225] op_sel_hi:[1,0]
	v_pk_mul_f32 v[228:229], v[180:181], v[224:225] op_sel_hi:[1,0]
	v_cvt_pk_bf16_f32 v230, v226, v227
	v_cvt_pk_bf16_f32 v231, v228, v229
	global_store_dwordx2 v221, v[230:231], s[100:101] offset:3072
	v_pk_mul_f32 v[226:227], v[154:155], v[224:225] op_sel_hi:[1,0]
	v_pk_mul_f32 v[228:229], v[156:157], v[224:225] op_sel_hi:[1,0]
	v_cvt_pk_bf16_f32 v202, v226, v227
	v_cvt_pk_bf16_f32 v203, v228, v229
	global_store_dwordx2 v221, v[202:203], s[100:101] offset:3584
	ds_read_b128 v[178:181], v255
	ds_read_b128 v[154:157], v255 offset:1024
	s_waitcnt lgkmcnt(0)

; #define PG8_WAIT_V(n) asm volatile("s_waitcnt vmcnt(" #n ")" ::: "memory")
; #define PG8_BAR __builtin_amdgcn_s_barrier()
; template <class Epi, class Sched>
; __device__ __forceinline__ void gemm_phase(LAS unsigned char* lds, const Sched& S, const Epi& E, bool natural = false) {
;     ...
;     PG8_WAIT_V(0);
;     PG8_BAR;
.LBB0_211:
	s_waitcnt vmcnt(0)
	s_barrier
	s_cmp_lt_i32 s99, 0
	s_cbranch_scc1 .Lax_nosig_z
	v_readfirstlane_b32 s100, v190
	s_nop 0
	s_cmp_lt_u32 s100, 64
	s_cbranch_scc0 .Lax_sigdone_z
	s_lshl_b32 s100, s99, 4
	s_add_u32 s100, s100, s92
	s_addc_u32 s101, s93, 0
	s_add_u32 s100, s100, 0x3800
	s_addc_u32 s101, s101, 0
	v_mov_b32_e32 v254, 0
	v_mov_b32_e32 v255, 1
	s_mov_b64 exec, 1
	global_atomic_add v254, v255, s[100:101]
	s_mov_b64 exec, -1

; __device__ __forceinline__ unsigned xb_ld(unsigned* p)              { return __hip_atomic_load(p, __ATOMIC_RELAXED, __HIP_MEMORY_SCOPE_AGENT); }
; __device__ __forceinline__ void xcd_barrier_complete(unsigned* bar, unsigned x, unsigned& nloc, unsigned& nx) {
;     const unsigned G = gridDim.x * gridDim.y * gridDim.z;
;     unsigned sum, cnt, mine, sp = 0u;
;     for (;;) {
;         sum = 0u; cnt = 0u; mine = 0u;
; #pragma unroll
;         for (unsigned j = 0; j < 16; ++j) { const unsigned c = xb_ld(&bar[XB_XCNT(j)]); sum += c; cnt += (c > 0u) ? 1u : 0u; mine = (j == x) ? c : mine; }
; __device__ __forceinline__ void xcd_barrier(const XcdBarrier& b) {
;     asm volatile("s_waitcnt vmcnt(0)" ::: "memory");
;     __syncthreads();
;     if (threadIdx.x == 0) {
;         unsigned* bar = b.bar;
;         __builtin_amdgcn_s_waitcnt(0);
;         unsigned nloc = b.st[0], nx = b.st[1];
;         if (nloc == 0u) { xcd_barrier_complete(bar, b.x, nloc, nx); b.st[0] = nloc; b.st[1] = nx; }
.Lax_nosig_z:
.LBB0_212:
	s_cmp_gt_i32 s67, 2
	s_cselect_b64 s[0:1], -1, 0
	s_and_b64 s[4:5], s[6:7], s[0:1]
	s_andn2_b64 vcc, exec, s[4:5]
	s_cbranch_vccnz .LBB0_266
	s_getreg_b32 s6, hwreg(HW_REG_XCC_ID, 0, 4)
	s_waitcnt vmcnt(0)
	s_waitcnt vmcnt(0) lgkmcnt(0)
	s_barrier
	s_and_saveexec_b64 s[4:5], s[94:95]
	s_cbranch_execz .LBB0_265
	s_add_i32 s7, 0, 0x25fc0
	v_mov_b32_e32 v0, s7
	s_waitcnt vmcnt(0) expcnt(0) lgkmcnt(0)
	ds_read_b32 v2, v0
	s_add_i32 s7, 0, 0x25fc4
	v_mov_b32_e32 v0, s7
	ds_read_b32 v0, v0
	s_and_b32 s33, s6, 15
	s_waitcnt lgkmcnt(1)
	v_cmp_ne_u32_e32 vcc, 0, v2
	s_cbranch_vccnz .LBB0_229
	s_load_dwordx2 s[10:11], s[74:75], 0x80
	s_load_dword s9, s[74:75], 0x88
	s_add_u32 s6, s64, 0xaf0200
	s_addc_u32 s7, s65, 0
	s_add_u32 s8, s64, 0xaf0400
	s_waitcnt lgkmcnt(0)
	s_mul_i32 s49, s11, s10
	s_mul_i32 s49, s49, s9
	s_addc_u32 s9, s65, 0
	s_add_u32 s10, s64, 0xaf0500
	s_addc_u32 s11, s65, 0
	s_add_u32 s12, s64, 0xaf0600
	s_addc_u32 s13, s65, 0
	s_add_u32 s14, s64, 0xaf0700
	s_addc_u32 s15, s65, 0
	s_add_u32 s16, s64, 0xaf0800
	s_addc_u32 s17, s65, 0
	s_add_u32 s18, s64, 0xaf0900
	s_addc_u32 s19, s65, 0
	s_add_u32 s20, s64, 0xaf0a00
	s_addc_u32 s21, s65, 0
	s_add_u32 s22, s64, 0xaf0b00
	s_addc_u32 s23, s65, 0
	s_add_u32 s24, s64, 0xaf0c00
	s_addc_u32 s25, s65, 0
	s_add_u32 s26, s64, 0xaf0d00
	s_addc_u32 s27, s65, 0
	s_add_u32 s28, s64, 0xaf0e00
	s_addc_u32 s29, s65, 0
	s_add_u32 s30, s64, 0xaf0f00
	s_addc_u32 s31, s65, 0
	s_add_u32 s34, s64, 0xaf1000
	s_addc_u32 s35, s65, 0
	s_add_u32 s36, s64, 0xaf1100
	s_addc_u32 s37, s65, 0
	s_add_u32 s38, s64, 0xaf1200
	s_addc_u32 s39, s65, 0
	s_add_u32 s40, s64, 0xaf1300
	s_addc_u32 s41, s65, 0
	s_mov_b32 s50, 1
	v_mov_b32_e32 v16, 0
	s_branch .LBB0_217

; #define LAS __attribute__((address_space(3)))
; __global__ void __launch_bounds__(512, 2) fwd_kernel(Args a) {
;     extern __shared__ __attribute__((aligned(16))) unsigned char lds_raw[];
;     LAS unsigned char* lds = (LAS unsigned char*)lds_raw;
;     const int tid = threadIdx.x, lane = tid & 63, wave = __builtin_amdgcn_readfirstlane(tid >> 6);
	.amdhsa_kernel _Z10fwd_kernel4Args
		.amdhsa_group_segment_fixed_size 0
		.amdhsa_private_segment_fixed_size 0
		.amdhsa_kernarg_size 384
		.amdhsa_user_sgpr_count 2
		.amdhsa_user_sgpr_dispatch_ptr 0
		.amdhsa_user_sgpr_queue_ptr 0
		.amdhsa_user_sgpr_kernarg_segment_ptr 1
		.amdhsa_user_sgpr_dispatch_id 0
		.amdhsa_user_sgpr_kernarg_preload_length 0
		.amdhsa_user_sgpr_kernarg_preload_offset 0
		.amdhsa_user_sgpr_private_segment_size 0
		.amdhsa_uses_dynamic_stack 0
		.amdhsa_enable_private_segment 0
		.amdhsa_system_sgpr_workgroup_id_x 1
		.amdhsa_system_sgpr_workgroup_id_y 0
		.amdhsa_system_sgpr_workgroup_id_z 0
		.amdhsa_system_sgpr_workgroup_info 0
		.amdhsa_system_vgpr_workitem_id 2
		.amdhsa_next_free_vgpr 256
		.amdhsa_next_free_sgpr 102
		.amdhsa_accum_offset 256
		.amdhsa_reserve_vcc 1
		.amdhsa_float_round_mode_32 0
		.amdhsa_float_round_mode_16_64 0
		.amdhsa_float_denorm_mode_32 3
		.amdhsa_float_denorm_mode_16_64 3
		.amdhsa_dx10_clamp 1
		.amdhsa_ieee_mode 1
		.amdhsa_fp16_overflow 0
		.amdhsa_tg_split 0
		.amdhsa_exception_fp_ieee_invalid_op 0
		.amdhsa_exception_fp_denorm_src 0
		.amdhsa_exception_fp_ieee_div_zero 0
		.amdhsa_exception_fp_ieee_overflow 0
		.amdhsa_exception_fp_ieee_underflow 0
		.amdhsa_exception_fp_ieee_inexact 0
		.amdhsa_exception_int_div_zero 0
	.end_amdhsa_kernel

; #define LAS __attribute__((address_space(3)))
; __global__ void __launch_bounds__(512, 2) fwd_kernel(Args a) {
;     extern __shared__ __attribute__((aligned(16))) unsigned char lds_raw[];
;     LAS unsigned char* lds = (LAS unsigned char*)lds_raw;
;     const int tid = threadIdx.x, lane = tid & 63, wave = __builtin_amdgcn_readfirstlane(tid >> 6);
amdhsa.kernels:
  - .agpr_count:     0
    .args:
      - .offset:         0
        .size:           128
        .value_kind:     by_value
      - .offset:         128
        .size:           4
        .value_kind:     hidden_block_count_x
      - .offset:         132
        .size:           4
        .value_kind:     hidden_block_count_y
      - .offset:         136
        .size:           4
        .value_kind:     hidden_block_count_z
      - .offset:         140
        .size:           2
        .value_kind:     hidden_group_size_x
      - .offset:         142
        .size:           2
        .value_kind:     hidden_group_size_y
      - .offset:         144
        .size:           2
        .value_kind:     hidden_group_size_z
      - .offset:         146
        .size:           2
        .value_kind:     hidden_remainder_x
      - .offset:         148
        .size:           2
        .value_kind:     hidden_remainder_y
      - .offset:         150
        .size:           2
        .value_kind:     hidden_remainder_z
      - .offset:         168
        .size:           8
        .value_kind:     hidden_global_offset_x
      - .offset:         176
        .size:           8
        .value_kind:     hidden_global_offset_y
      - .offset:         184
        .size:           8
        .value_kind:     hidden_global_offset_z
      - .offset:         192
        .size:           2
        .value_kind:     hidden_grid_dims
      - .offset:         216
        .size:           8
        .value_kind:     hidden_multigrid_sync_arg
      - .offset:         248
        .size:           4
        .value_kind:     hidden_dynamic_lds_size
    .group_segment_fixed_size: 0
    .kernarg_segment_align: 8
    .kernarg_segment_size: 384
    .language:       OpenCL C
    .language_version:
      - 2
      - 0
    .max_flat_workgroup_size: 512
    .name:           _Z10fwd_kernel4Args
    .private_segment_fixed_size: 0
    .sgpr_count:     108
    .sgpr_spill_count: 102
    .symbol:         _Z10fwd_kernel4Args.kd
    .uniform_work_group_size: 1
    .uses_dynamic_stack: false
    .vgpr_count:     256
    .vgpr_spill_count: 0
    .wavefront_size: 64
